# RWKV prompt loop: next-batch loads issued before the LDS barrier, flush store deferred; static placement iv; hand step block
# speedup vs baseline: 1.0057x; 1.0057x over previous
.LBB0_406:
	s_or_b64 exec, exec, s[0:1]
	v_bfe_u32 v80, v84, 4, 2
	v_and_b32_e32 v81, -4, v83
	v_lshlrev_b32_e32 v91, 2, v81
	v_lshlrev_b32_e32 v92, 2, v80
	v_add3_u32 v88, 0, v91, v92
	v_add_u32_e32 v21, 0x5000, v88
	v_lshl_add_u32 v82, v34, 2, 0
	ds_read2_b32 v[26:27], v21 offset1:16
	ds_read_b128 v[16:19], v82 offset:12288
	ds_read_b128 v[22:25], v82
	ds_read_b128 v[50:53], v82 offset:256
	ds_read_b128 v[54:57], v82 offset:4096
	ds_read_b128 v[58:61], v82 offset:4352
	ds_read_b128 v[62:65], v82 offset:8192
	ds_read_b128 v[66:69], v82 offset:8448
	ds_read_b128 v[94:97], v82 offset:12544
	ds_read_b128 v[98:101], v82 offset:16384
	ds_read_b128 v[102:105], v82 offset:16640
	s_waitcnt lgkmcnt(9)
	v_pk_mul_f32 v[18:19], v[18:19], 0 op_sel_hi:[1,0]
	v_cmp_eq_u32_e64 s[0:1], 0, v79
	v_pk_fma_f32 v[16:17], v[16:17], 0, v[18:19] op_sel_hi:[1,0,1]
	v_mov_b32_e32 v20, v27
	v_add_f32_e32 v16, v16, v17
	s_nop 1
	v_add_f32_dpp v16, v16, v16 row_ror:8 row_mask:0xf bank_mask:0xf bound_ctrl:1
	s_nop 1
	v_add_f32_dpp v16, v16, v16 row_ror:4 row_mask:0xf bank_mask:0xf bound_ctrl:1
	s_nop 1
	v_add_f32_dpp v16, v16, v16 row_ror:2 row_mask:0xf bank_mask:0xf bound_ctrl:1
	s_nop 1
	v_add_f32_dpp v16, v16, v16 row_ror:1 row_mask:0xf bank_mask:0xf bound_ctrl:1
	s_waitcnt lgkmcnt(1)
	v_pk_mul_f32 v[18:19], v[98:99], v[16:17] op_sel_hi:[1,0]
	v_pk_mul_f32 v[16:17], v[100:101], v[16:17] op_sel_hi:[1,0]
	v_pk_fma_f32 v[18:19], v[26:27], v[54:55], v[18:19] op_sel_hi:[0,1,1] neg_lo:[0,0,1] neg_hi:[0,0,1]
	v_pk_fma_f32 v[16:17], v[26:27], v[56:57], v[16:17] op_sel_hi:[0,1,1] neg_lo:[0,0,1] neg_hi:[0,0,1]
	v_pk_fma_f32 v[54:55], v[64:65], 0, v[16:17] op_sel_hi:[1,0,1]
	v_pk_fma_f32 v[18:19], v[62:63], 0, v[18:19] op_sel_hi:[1,0,1]
	v_pk_mul_f32 v[16:17], v[24:25], v[54:55]
	s_nop 0
	v_pk_fma_f32 v[16:17], v[22:23], v[18:19], v[16:17]
	s_nop 0
	v_add_f32_e32 v26, v16, v17
	v_pk_mul_f32 v[16:17], v[96:97], v[54:55]
	s_nop 0
	v_pk_fma_f32 v[16:17], v[94:95], v[18:19], v[16:17]
	s_nop 0
	v_add_f32_e32 v16, v16, v17
	s_nop 1
	v_add_f32_dpp v16, v16, v16 row_ror:8 row_mask:0xf bank_mask:0xf bound_ctrl:1
	s_nop 1
	v_add_f32_dpp v16, v16, v16 row_ror:4 row_mask:0xf bank_mask:0xf bound_ctrl:1
	s_nop 1
	v_add_f32_dpp v16, v16, v16 row_ror:2 row_mask:0xf bank_mask:0xf bound_ctrl:1
	s_nop 1
	v_add_f32_dpp v16, v16, v16 row_ror:1 row_mask:0xf bank_mask:0xf bound_ctrl:1
	s_waitcnt lgkmcnt(0)
	v_pk_mul_f32 v[22:23], v[102:103], v[16:17] op_sel_hi:[1,0]
	v_pk_mul_f32 v[16:17], v[104:105], v[16:17] op_sel_hi:[1,0]
	v_pk_fma_f32 v[22:23], v[20:21], v[58:59], v[22:23] op_sel_hi:[0,1,1] neg_lo:[0,0,1] neg_hi:[0,0,1]
	v_pk_fma_f32 v[24:25], v[20:21], v[60:61], v[16:17] op_sel_hi:[0,1,1] neg_lo:[0,0,1] neg_hi:[0,0,1]
	v_pk_fma_f32 v[16:17], v[66:67], v[18:19], v[22:23]
	v_pk_fma_f32 v[18:19], v[68:69], v[54:55], v[24:25]
	v_mov_b32_e32 v25, v28
	v_pk_mul_f32 v[22:23], v[52:53], v[18:19]
	s_nop 0
	v_pk_fma_f32 v[22:23], v[50:51], v[16:17], v[22:23]
	s_nop 0
	v_add_f32_e32 v20, v22, v23
	v_add_f32_dpp v22, v26, v26 row_ror:8 row_mask:0xf bank_mask:0xf bound_ctrl:1
	v_mov_b32_e32 v23, v28
	v_add_f32_dpp v20, v20, v20 row_ror:8 row_mask:0xf bank_mask:0xf bound_ctrl:1
	v_add_f32_dpp v22, v22, v22 row_ror:4 row_mask:0xf bank_mask:0xf bound_ctrl:1
	s_nop 0
	v_add_f32_dpp v20, v20, v20 row_ror:4 row_mask:0xf bank_mask:0xf bound_ctrl:1
	v_add_f32_dpp v22, v22, v22 row_ror:2 row_mask:0xf bank_mask:0xf bound_ctrl:1
	s_nop 0
	v_add_f32_dpp v24, v20, v20 row_ror:2 row_mask:0xf bank_mask:0xf bound_ctrl:1
	v_mov_b32_dpp v23, v22 row_ror:1 row_mask:0xf bank_mask:0xf
	v_add_u32_e32 v20, 0x5400, v88
	v_mov_b32_dpp v25, v24 row_ror:1 row_mask:0xf bank_mask:0xf
	s_and_saveexec_b64 s[4:5], s[0:1]
	v_add_f32_e32 v22, v22, v23
	v_add_f32_e32 v23, v24, v25
	ds_write2_b32 v20, v22, v23 offset1:16
	s_or_b64 exec, exec, s[4:5]
	ds_read2_b32 v[26:27], v21 offset0:32 offset1:48
	ds_read_b128 v[22:25], v82 offset:12800
	ds_read_b128 v[50:53], v82 offset:512
	ds_read_b128 v[54:57], v82 offset:768
	ds_read_b128 v[58:61], v82 offset:4608
	ds_read_b128 v[62:65], v82 offset:4864
	ds_read_b128 v[66:69], v82 offset:8704
	ds_read_b128 v[94:97], v82 offset:8960
	ds_read_b128 v[98:101], v82 offset:13056
	ds_read_b128 v[102:105], v82 offset:16896
	ds_read_b128 v[106:109], v82 offset:17152
	s_waitcnt lgkmcnt(9)
	v_pk_mul_f32 v[24:25], v[18:19], v[24:25]
	s_nop 0
	v_pk_fma_f32 v[22:23], v[16:17], v[22:23], v[24:25]
	s_nop 0
	v_add_f32_e32 v22, v22, v23
	s_nop 1
	v_add_f32_dpp v22, v22, v22 row_ror:8 row_mask:0xf bank_mask:0xf bound_ctrl:1
	s_nop 1
	v_add_f32_dpp v22, v22, v22 row_ror:4 row_mask:0xf bank_mask:0xf bound_ctrl:1
	s_nop 1
	v_add_f32_dpp v22, v22, v22 row_ror:2 row_mask:0xf bank_mask:0xf bound_ctrl:1
	s_nop 1
	v_add_f32_dpp v22, v22, v22 row_ror:1 row_mask:0xf bank_mask:0xf bound_ctrl:1
	s_waitcnt lgkmcnt(1)
	v_pk_mul_f32 v[24:25], v[102:103], v[22:23] op_sel_hi:[1,0]
	v_pk_mul_f32 v[22:23], v[104:105], v[22:23] op_sel_hi:[1,0]
	v_pk_fma_f32 v[24:25], v[26:27], v[58:59], v[24:25] op_sel_hi:[0,1,1] neg_lo:[0,0,1] neg_hi:[0,0,1]
	v_pk_fma_f32 v[22:23], v[26:27], v[60:61], v[22:23] op_sel_hi:[0,1,1] neg_lo:[0,0,1] neg_hi:[0,0,1]
	v_pk_fma_f32 v[18:19], v[18:19], v[68:69], v[22:23]
	v_pk_fma_f32 v[16:17], v[16:17], v[66:67], v[24:25]
	v_pk_mul_f32 v[22:23], v[52:53], v[18:19]
	v_mov_b32_e32 v24, v27
	v_pk_fma_f32 v[22:23], v[50:51], v[16:17], v[22:23]
	s_nop 0
	v_add_f32_e32 v25, v22, v23
	v_pk_mul_f32 v[22:23], v[100:101], v[18:19]
	s_nop 0
	v_pk_fma_f32 v[22:23], v[98:99], v[16:17], v[22:23]
	s_nop 0
	v_add_f32_e32 v22, v22, v23
	s_nop 1
	v_add_f32_dpp v22, v22, v22 row_ror:8 row_mask:0xf bank_mask:0xf bound_ctrl:1
	s_nop 1
	v_add_f32_dpp v22, v22, v22 row_ror:4 row_mask:0xf bank_mask:0xf bound_ctrl:1
	s_nop 1
	v_add_f32_dpp v22, v22, v22 row_ror:2 row_mask:0xf bank_mask:0xf bound_ctrl:1
	s_nop 1
	v_add_f32_dpp v22, v22, v22 row_ror:1 row_mask:0xf bank_mask:0xf bound_ctrl:1
	s_waitcnt lgkmcnt(0)
	v_pk_mul_f32 v[26:27], v[106:107], v[22:23] op_sel_hi:[1,0]
	v_pk_mul_f32 v[22:23], v[108:109], v[22:23] op_sel_hi:[1,0]
	v_pk_fma_f32 v[26:27], v[24:25], v[62:63], v[26:27] op_sel_hi:[0,1,1] neg_lo:[0,0,1] neg_hi:[0,0,1]
	v_pk_fma_f32 v[22:23], v[24:25], v[64:65], v[22:23] op_sel_hi:[0,1,1] neg_lo:[0,0,1] neg_hi:[0,0,1]
	v_pk_fma_f32 v[18:19], v[96:97], v[18:19], v[22:23]
	v_pk_fma_f32 v[16:17], v[94:95], v[16:17], v[26:27]
	v_pk_mul_f32 v[22:23], v[56:57], v[18:19]
	s_nop 0
	v_pk_fma_f32 v[22:23], v[54:55], v[16:17], v[22:23]
	s_nop 0
	v_add_f32_e32 v24, v22, v23
	v_add_f32_dpp v22, v25, v25 row_ror:8 row_mask:0xf bank_mask:0xf bound_ctrl:1
	v_mov_b32_e32 v23, v28
	v_add_f32_dpp v24, v24, v24 row_ror:8 row_mask:0xf bank_mask:0xf bound_ctrl:1
	v_add_f32_dpp v22, v22, v22 row_ror:4 row_mask:0xf bank_mask:0xf bound_ctrl:1
	v_mov_b32_e32 v25, v28
	v_add_f32_dpp v24, v24, v24 row_ror:4 row_mask:0xf bank_mask:0xf bound_ctrl:1
	v_add_f32_dpp v22, v22, v22 row_ror:2 row_mask:0xf bank_mask:0xf bound_ctrl:1
	s_nop 0
	v_add_f32_dpp v24, v24, v24 row_ror:2 row_mask:0xf bank_mask:0xf bound_ctrl:1
	v_mov_b32_dpp v23, v22 row_ror:1 row_mask:0xf bank_mask:0xf
	s_nop 0
	v_mov_b32_dpp v25, v24 row_ror:1 row_mask:0xf bank_mask:0xf
	s_and_saveexec_b64 s[4:5], s[0:1]
	v_add_f32_e32 v22, v22, v23
	v_add_f32_e32 v23, v24, v25
	ds_write2_b32 v20, v22, v23 offset0:32 offset1:48
	s_or_b64 exec, exec, s[4:5]
	ds_read2_b32 v[26:27], v21 offset0:64 offset1:80
	ds_read_b128 v[22:25], v82 offset:13312
	ds_read_b128 v[50:53], v82 offset:1024
	ds_read_b128 v[54:57], v82 offset:1280
	ds_read_b128 v[58:61], v82 offset:5120
	ds_read_b128 v[62:65], v82 offset:5376
	ds_read_b128 v[66:69], v82 offset:9216
	ds_read_b128 v[94:97], v82 offset:9472
	ds_read_b128 v[98:101], v82 offset:13568
	ds_read_b128 v[102:105], v82 offset:17408
	ds_read_b128 v[106:109], v82 offset:17664
	s_waitcnt lgkmcnt(9)
	v_pk_mul_f32 v[24:25], v[18:19], v[24:25]
	s_nop 0
	v_pk_fma_f32 v[22:23], v[16:17], v[22:23], v[24:25]
	s_nop 0
	v_add_f32_e32 v22, v22, v23
	s_nop 1
	v_add_f32_dpp v22, v22, v22 row_ror:8 row_mask:0xf bank_mask:0xf bound_ctrl:1
	s_nop 1
	v_add_f32_dpp v22, v22, v22 row_ror:4 row_mask:0xf bank_mask:0xf bound_ctrl:1
	s_nop 1
	v_add_f32_dpp v22, v22, v22 row_ror:2 row_mask:0xf bank_mask:0xf bound_ctrl:1
	s_nop 1
	v_add_f32_dpp v22, v22, v22 row_ror:1 row_mask:0xf bank_mask:0xf bound_ctrl:1
	s_waitcnt lgkmcnt(1)
	v_pk_mul_f32 v[24:25], v[102:103], v[22:23] op_sel_hi:[1,0]
	v_pk_mul_f32 v[22:23], v[104:105], v[22:23] op_sel_hi:[1,0]
	v_pk_fma_f32 v[24:25], v[26:27], v[58:59], v[24:25] op_sel_hi:[0,1,1] neg_lo:[0,0,1] neg_hi:[0,0,1]
	v_pk_fma_f32 v[22:23], v[26:27], v[60:61], v[22:23] op_sel_hi:[0,1,1] neg_lo:[0,0,1] neg_hi:[0,0,1]
	v_pk_fma_f32 v[18:19], v[18:19], v[68:69], v[22:23]
	v_pk_fma_f32 v[16:17], v[16:17], v[66:67], v[24:25]
	v_pk_mul_f32 v[22:23], v[52:53], v[18:19]
	v_mov_b32_e32 v24, v27
	v_pk_fma_f32 v[22:23], v[50:51], v[16:17], v[22:23]
	s_nop 0
	v_add_f32_e32 v25, v22, v23
	v_pk_mul_f32 v[22:23], v[100:101], v[18:19]
	s_nop 0
	v_pk_fma_f32 v[22:23], v[98:99], v[16:17], v[22:23]
	s_nop 0
	v_add_f32_e32 v22, v22, v23
	s_nop 1
	v_add_f32_dpp v22, v22, v22 row_ror:8 row_mask:0xf bank_mask:0xf bound_ctrl:1
	s_nop 1
	v_add_f32_dpp v22, v22, v22 row_ror:4 row_mask:0xf bank_mask:0xf bound_ctrl:1
	s_nop 1
	v_add_f32_dpp v22, v22, v22 row_ror:2 row_mask:0xf bank_mask:0xf bound_ctrl:1
	s_nop 1
	v_add_f32_dpp v22, v22, v22 row_ror:1 row_mask:0xf bank_mask:0xf bound_ctrl:1
	s_waitcnt lgkmcnt(0)
	v_pk_mul_f32 v[26:27], v[106:107], v[22:23] op_sel_hi:[1,0]
	v_pk_mul_f32 v[22:23], v[108:109], v[22:23] op_sel_hi:[1,0]
	v_pk_fma_f32 v[26:27], v[24:25], v[62:63], v[26:27] op_sel_hi:[0,1,1] neg_lo:[0,0,1] neg_hi:[0,0,1]
	v_pk_fma_f32 v[22:23], v[24:25], v[64:65], v[22:23] op_sel_hi:[0,1,1] neg_lo:[0,0,1] neg_hi:[0,0,1]
	v_pk_fma_f32 v[18:19], v[96:97], v[18:19], v[22:23]
	v_pk_fma_f32 v[16:17], v[94:95], v[16:17], v[26:27]
	v_pk_mul_f32 v[22:23], v[56:57], v[18:19]
	s_nop 0
	v_pk_fma_f32 v[22:23], v[54:55], v[16:17], v[22:23]
	s_nop 0
	v_add_f32_e32 v24, v22, v23
	v_add_f32_dpp v22, v25, v25 row_ror:8 row_mask:0xf bank_mask:0xf bound_ctrl:1
	v_mov_b32_e32 v23, v28
	v_add_f32_dpp v24, v24, v24 row_ror:8 row_mask:0xf bank_mask:0xf bound_ctrl:1
	v_add_f32_dpp v22, v22, v22 row_ror:4 row_mask:0xf bank_mask:0xf bound_ctrl:1
	v_mov_b32_e32 v25, v28
	v_add_f32_dpp v24, v24, v24 row_ror:4 row_mask:0xf bank_mask:0xf bound_ctrl:1
	v_add_f32_dpp v22, v22, v22 row_ror:2 row_mask:0xf bank_mask:0xf bound_ctrl:1
	s_nop 0
	v_add_f32_dpp v24, v24, v24 row_ror:2 row_mask:0xf bank_mask:0xf bound_ctrl:1
	v_mov_b32_dpp v23, v22 row_ror:1 row_mask:0xf bank_mask:0xf
	s_nop 0
	v_mov_b32_dpp v25, v24 row_ror:1 row_mask:0xf bank_mask:0xf
	s_and_saveexec_b64 s[4:5], s[0:1]
	v_add_f32_e32 v22, v22, v23
	v_add_f32_e32 v23, v24, v25
	ds_write2_b32 v20, v22, v23 offset0:64 offset1:80
	s_or_b64 exec, exec, s[4:5]
	ds_read2_b32 v[26:27], v21 offset0:96 offset1:112
	ds_read_b128 v[22:25], v82 offset:13824
	ds_read_b128 v[50:53], v82 offset:1536
	ds_read_b128 v[54:57], v82 offset:1792
	ds_read_b128 v[58:61], v82 offset:5632
	ds_read_b128 v[62:65], v82 offset:5888
	ds_read_b128 v[66:69], v82 offset:9728
	ds_read_b128 v[94:97], v82 offset:9984
	ds_read_b128 v[98:101], v82 offset:14080
	ds_read_b128 v[102:105], v82 offset:17920
	ds_read_b128 v[106:109], v82 offset:18176
	s_waitcnt lgkmcnt(9)
	v_pk_mul_f32 v[24:25], v[18:19], v[24:25]
	s_nop 0
	v_pk_fma_f32 v[22:23], v[16:17], v[22:23], v[24:25]
	s_nop 0
	v_add_f32_e32 v22, v22, v23
	s_nop 1
	v_add_f32_dpp v22, v22, v22 row_ror:8 row_mask:0xf bank_mask:0xf bound_ctrl:1
	s_nop 1
	v_add_f32_dpp v22, v22, v22 row_ror:4 row_mask:0xf bank_mask:0xf bound_ctrl:1
	s_nop 1
	v_add_f32_dpp v22, v22, v22 row_ror:2 row_mask:0xf bank_mask:0xf bound_ctrl:1
	s_nop 1
	v_add_f32_dpp v22, v22, v22 row_ror:1 row_mask:0xf bank_mask:0xf bound_ctrl:1
	s_waitcnt lgkmcnt(1)
	v_pk_mul_f32 v[24:25], v[102:103], v[22:23] op_sel_hi:[1,0]
	v_pk_mul_f32 v[22:23], v[104:105], v[22:23] op_sel_hi:[1,0]
	v_pk_fma_f32 v[24:25], v[26:27], v[58:59], v[24:25] op_sel_hi:[0,1,1] neg_lo:[0,0,1] neg_hi:[0,0,1]
	v_pk_fma_f32 v[22:23], v[26:27], v[60:61], v[22:23] op_sel_hi:[0,1,1] neg_lo:[0,0,1] neg_hi:[0,0,1]
	v_pk_fma_f32 v[18:19], v[18:19], v[68:69], v[22:23]
	v_pk_fma_f32 v[16:17], v[16:17], v[66:67], v[24:25]
	v_pk_mul_f32 v[22:23], v[52:53], v[18:19]
	v_mov_b32_e32 v24, v27
	v_pk_fma_f32 v[22:23], v[50:51], v[16:17], v[22:23]
	s_nop 0
	v_add_f32_e32 v25, v22, v23
	v_pk_mul_f32 v[22:23], v[100:101], v[18:19]
	s_nop 0
	v_pk_fma_f32 v[22:23], v[98:99], v[16:17], v[22:23]
	s_nop 0
	v_add_f32_e32 v22, v22, v23
	s_nop 1
	v_add_f32_dpp v22, v22, v22 row_ror:8 row_mask:0xf bank_mask:0xf bound_ctrl:1
	s_nop 1
	v_add_f32_dpp v22, v22, v22 row_ror:4 row_mask:0xf bank_mask:0xf bound_ctrl:1
	s_nop 1
	v_add_f32_dpp v22, v22, v22 row_ror:2 row_mask:0xf bank_mask:0xf bound_ctrl:1
	s_nop 1
	v_add_f32_dpp v22, v22, v22 row_ror:1 row_mask:0xf bank_mask:0xf bound_ctrl:1
	s_waitcnt lgkmcnt(0)
	v_pk_mul_f32 v[26:27], v[106:107], v[22:23] op_sel_hi:[1,0]
	v_pk_mul_f32 v[22:23], v[108:109], v[22:23] op_sel_hi:[1,0]
	v_pk_fma_f32 v[26:27], v[24:25], v[62:63], v[26:27] op_sel_hi:[0,1,1] neg_lo:[0,0,1] neg_hi:[0,0,1]
	v_pk_fma_f32 v[22:23], v[24:25], v[64:65], v[22:23] op_sel_hi:[0,1,1] neg_lo:[0,0,1] neg_hi:[0,0,1]
	v_pk_fma_f32 v[18:19], v[96:97], v[18:19], v[22:23]
	v_pk_fma_f32 v[16:17], v[94:95], v[16:17], v[26:27]
	v_pk_mul_f32 v[22:23], v[56:57], v[18:19]
	s_nop 0
	v_pk_fma_f32 v[22:23], v[54:55], v[16:17], v[22:23]
	s_nop 0
	v_add_f32_e32 v24, v22, v23
	v_add_f32_dpp v22, v25, v25 row_ror:8 row_mask:0xf bank_mask:0xf bound_ctrl:1
	v_mov_b32_e32 v23, v28
	v_add_f32_dpp v24, v24, v24 row_ror:8 row_mask:0xf bank_mask:0xf bound_ctrl:1
	v_add_f32_dpp v22, v22, v22 row_ror:4 row_mask:0xf bank_mask:0xf bound_ctrl:1
	v_mov_b32_e32 v25, v28
	v_add_f32_dpp v24, v24, v24 row_ror:4 row_mask:0xf bank_mask:0xf bound_ctrl:1
	v_add_f32_dpp v22, v22, v22 row_ror:2 row_mask:0xf bank_mask:0xf bound_ctrl:1
	s_nop 0
	v_add_f32_dpp v24, v24, v24 row_ror:2 row_mask:0xf bank_mask:0xf bound_ctrl:1
	v_mov_b32_dpp v23, v22 row_ror:1 row_mask:0xf bank_mask:0xf
	s_nop 0
	v_mov_b32_dpp v25, v24 row_ror:1 row_mask:0xf bank_mask:0xf
	s_and_saveexec_b64 s[4:5], s[0:1]
	v_add_f32_e32 v22, v22, v23
	v_add_f32_e32 v23, v24, v25
	ds_write2_b32 v20, v22, v23 offset0:96 offset1:112
	s_or_b64 exec, exec, s[4:5]
	ds_read2_b32 v[26:27], v21 offset0:128 offset1:144
	ds_read_b128 v[22:25], v82 offset:14336
	ds_read_b128 v[50:53], v82 offset:2048
	ds_read_b128 v[54:57], v82 offset:2304
	ds_read_b128 v[58:61], v82 offset:6144
	ds_read_b128 v[62:65], v82 offset:6400
	ds_read_b128 v[66:69], v82 offset:10240
	ds_read_b128 v[94:97], v82 offset:10496
	ds_read_b128 v[98:101], v82 offset:14592
	ds_read_b128 v[102:105], v82 offset:18432
	ds_read_b128 v[106:109], v82 offset:18688
	s_waitcnt lgkmcnt(9)
	v_pk_mul_f32 v[24:25], v[18:19], v[24:25]
	s_nop 0
	v_pk_fma_f32 v[22:23], v[16:17], v[22:23], v[24:25]
	s_nop 0
	v_add_f32_e32 v22, v22, v23
	s_nop 1
	v_add_f32_dpp v22, v22, v22 row_ror:8 row_mask:0xf bank_mask:0xf bound_ctrl:1
	s_nop 1
	v_add_f32_dpp v22, v22, v22 row_ror:4 row_mask:0xf bank_mask:0xf bound_ctrl:1
	s_nop 1
	v_add_f32_dpp v22, v22, v22 row_ror:2 row_mask:0xf bank_mask:0xf bound_ctrl:1
	s_nop 1
	v_add_f32_dpp v22, v22, v22 row_ror:1 row_mask:0xf bank_mask:0xf bound_ctrl:1
	s_waitcnt lgkmcnt(1)
	v_pk_mul_f32 v[24:25], v[102:103], v[22:23] op_sel_hi:[1,0]
	v_pk_mul_f32 v[22:23], v[104:105], v[22:23] op_sel_hi:[1,0]
	v_pk_fma_f32 v[24:25], v[26:27], v[58:59], v[24:25] op_sel_hi:[0,1,1] neg_lo:[0,0,1] neg_hi:[0,0,1]
	v_pk_fma_f32 v[22:23], v[26:27], v[60:61], v[22:23] op_sel_hi:[0,1,1] neg_lo:[0,0,1] neg_hi:[0,0,1]
	v_pk_fma_f32 v[18:19], v[18:19], v[68:69], v[22:23]
	v_pk_fma_f32 v[16:17], v[16:17], v[66:67], v[24:25]
	v_pk_mul_f32 v[22:23], v[52:53], v[18:19]
	v_mov_b32_e32 v24, v27
	v_pk_fma_f32 v[22:23], v[50:51], v[16:17], v[22:23]
	s_nop 0
	v_add_f32_e32 v25, v22, v23
	v_pk_mul_f32 v[22:23], v[100:101], v[18:19]
	s_nop 0
	v_pk_fma_f32 v[22:23], v[98:99], v[16:17], v[22:23]
	s_nop 0
	v_add_f32_e32 v22, v22, v23
	s_nop 1
	v_add_f32_dpp v22, v22, v22 row_ror:8 row_mask:0xf bank_mask:0xf bound_ctrl:1
	s_nop 1
	v_add_f32_dpp v22, v22, v22 row_ror:4 row_mask:0xf bank_mask:0xf bound_ctrl:1
	s_nop 1
	v_add_f32_dpp v22, v22, v22 row_ror:2 row_mask:0xf bank_mask:0xf bound_ctrl:1
	s_nop 1
	v_add_f32_dpp v22, v22, v22 row_ror:1 row_mask:0xf bank_mask:0xf bound_ctrl:1
	s_waitcnt lgkmcnt(0)
	v_pk_mul_f32 v[26:27], v[106:107], v[22:23] op_sel_hi:[1,0]
	v_pk_mul_f32 v[22:23], v[108:109], v[22:23] op_sel_hi:[1,0]
	v_pk_fma_f32 v[26:27], v[24:25], v[62:63], v[26:27] op_sel_hi:[0,1,1] neg_lo:[0,0,1] neg_hi:[0,0,1]
	v_pk_fma_f32 v[22:23], v[24:25], v[64:65], v[22:23] op_sel_hi:[0,1,1] neg_lo:[0,0,1] neg_hi:[0,0,1]
	v_pk_fma_f32 v[18:19], v[96:97], v[18:19], v[22:23]
	v_pk_fma_f32 v[16:17], v[94:95], v[16:17], v[26:27]
	v_pk_mul_f32 v[22:23], v[56:57], v[18:19]
	s_nop 0
	v_pk_fma_f32 v[22:23], v[54:55], v[16:17], v[22:23]
	s_nop 0
	v_add_f32_e32 v24, v22, v23
	v_add_f32_dpp v22, v25, v25 row_ror:8 row_mask:0xf bank_mask:0xf bound_ctrl:1
	v_mov_b32_e32 v23, v28
	v_add_f32_dpp v24, v24, v24 row_ror:8 row_mask:0xf bank_mask:0xf bound_ctrl:1
	v_add_f32_dpp v22, v22, v22 row_ror:4 row_mask:0xf bank_mask:0xf bound_ctrl:1
	v_mov_b32_e32 v25, v28
	v_add_f32_dpp v24, v24, v24 row_ror:4 row_mask:0xf bank_mask:0xf bound_ctrl:1
	v_add_f32_dpp v22, v22, v22 row_ror:2 row_mask:0xf bank_mask:0xf bound_ctrl:1
	s_nop 0
	v_add_f32_dpp v24, v24, v24 row_ror:2 row_mask:0xf bank_mask:0xf bound_ctrl:1
	v_mov_b32_dpp v23, v22 row_ror:1 row_mask:0xf bank_mask:0xf
	s_nop 0
	v_mov_b32_dpp v25, v24 row_ror:1 row_mask:0xf bank_mask:0xf
	s_and_saveexec_b64 s[4:5], s[0:1]
	v_add_f32_e32 v22, v22, v23
	v_add_f32_e32 v23, v24, v25
	ds_write2_b32 v20, v22, v23 offset0:128 offset1:144
	s_or_b64 exec, exec, s[4:5]
	ds_read2_b32 v[26:27], v21 offset0:160 offset1:176
	ds_read_b128 v[22:25], v82 offset:14848
	ds_read_b128 v[50:53], v82 offset:2560
	ds_read_b128 v[54:57], v82 offset:2816
	ds_read_b128 v[58:61], v82 offset:6656
	ds_read_b128 v[62:65], v82 offset:6912
	ds_read_b128 v[66:69], v82 offset:10752
	ds_read_b128 v[94:97], v82 offset:11008
	ds_read_b128 v[98:101], v82 offset:15104
	ds_read_b128 v[102:105], v82 offset:18944
	ds_read_b128 v[106:109], v82 offset:19200
	s_waitcnt lgkmcnt(9)
	v_pk_mul_f32 v[24:25], v[18:19], v[24:25]
	s_nop 0
	v_pk_fma_f32 v[22:23], v[16:17], v[22:23], v[24:25]
	s_nop 0
	v_add_f32_e32 v22, v22, v23
	s_nop 1
	v_add_f32_dpp v22, v22, v22 row_ror:8 row_mask:0xf bank_mask:0xf bound_ctrl:1
	s_nop 1
	v_add_f32_dpp v22, v22, v22 row_ror:4 row_mask:0xf bank_mask:0xf bound_ctrl:1
	s_nop 1
	v_add_f32_dpp v22, v22, v22 row_ror:2 row_mask:0xf bank_mask:0xf bound_ctrl:1
	s_nop 1
	v_add_f32_dpp v22, v22, v22 row_ror:1 row_mask:0xf bank_mask:0xf bound_ctrl:1
	s_waitcnt lgkmcnt(1)
	v_pk_mul_f32 v[24:25], v[102:103], v[22:23] op_sel_hi:[1,0]
	v_pk_mul_f32 v[22:23], v[104:105], v[22:23] op_sel_hi:[1,0]
	v_pk_fma_f32 v[24:25], v[26:27], v[58:59], v[24:25] op_sel_hi:[0,1,1] neg_lo:[0,0,1] neg_hi:[0,0,1]
	v_pk_fma_f32 v[22:23], v[26:27], v[60:61], v[22:23] op_sel_hi:[0,1,1] neg_lo:[0,0,1] neg_hi:[0,0,1]
	v_pk_fma_f32 v[18:19], v[18:19], v[68:69], v[22:23]
	v_pk_fma_f32 v[16:17], v[16:17], v[66:67], v[24:25]
	v_pk_mul_f32 v[22:23], v[52:53], v[18:19]
	v_mov_b32_e32 v24, v27
	v_pk_fma_f32 v[22:23], v[50:51], v[16:17], v[22:23]
	s_nop 0
	v_add_f32_e32 v25, v22, v23
	v_pk_mul_f32 v[22:23], v[100:101], v[18:19]
	s_nop 0
	v_pk_fma_f32 v[22:23], v[98:99], v[16:17], v[22:23]
	s_nop 0
	v_add_f32_e32 v22, v22, v23
	s_nop 1
	v_add_f32_dpp v22, v22, v22 row_ror:8 row_mask:0xf bank_mask:0xf bound_ctrl:1
	s_nop 1
	v_add_f32_dpp v22, v22, v22 row_ror:4 row_mask:0xf bank_mask:0xf bound_ctrl:1
	s_nop 1
	v_add_f32_dpp v22, v22, v22 row_ror:2 row_mask:0xf bank_mask:0xf bound_ctrl:1
	s_nop 1
	v_add_f32_dpp v22, v22, v22 row_ror:1 row_mask:0xf bank_mask:0xf bound_ctrl:1
	s_waitcnt lgkmcnt(0)
	v_pk_mul_f32 v[26:27], v[106:107], v[22:23] op_sel_hi:[1,0]
	v_pk_mul_f32 v[22:23], v[108:109], v[22:23] op_sel_hi:[1,0]
	v_pk_fma_f32 v[26:27], v[24:25], v[62:63], v[26:27] op_sel_hi:[0,1,1] neg_lo:[0,0,1] neg_hi:[0,0,1]
	v_pk_fma_f32 v[22:23], v[24:25], v[64:65], v[22:23] op_sel_hi:[0,1,1] neg_lo:[0,0,1] neg_hi:[0,0,1]
	v_pk_fma_f32 v[18:19], v[96:97], v[18:19], v[22:23]
	v_pk_fma_f32 v[16:17], v[94:95], v[16:17], v[26:27]
	v_pk_mul_f32 v[22:23], v[56:57], v[18:19]
	s_nop 0
	v_pk_fma_f32 v[22:23], v[54:55], v[16:17], v[22:23]
	s_nop 0
	v_add_f32_e32 v24, v22, v23
	v_add_f32_dpp v22, v25, v25 row_ror:8 row_mask:0xf bank_mask:0xf bound_ctrl:1
	v_mov_b32_e32 v23, v28
	v_add_f32_dpp v24, v24, v24 row_ror:8 row_mask:0xf bank_mask:0xf bound_ctrl:1
	v_add_f32_dpp v22, v22, v22 row_ror:4 row_mask:0xf bank_mask:0xf bound_ctrl:1
	v_mov_b32_e32 v25, v28
	v_add_f32_dpp v24, v24, v24 row_ror:4 row_mask:0xf bank_mask:0xf bound_ctrl:1
	v_add_f32_dpp v22, v22, v22 row_ror:2 row_mask:0xf bank_mask:0xf bound_ctrl:1
	s_nop 0
	v_add_f32_dpp v24, v24, v24 row_ror:2 row_mask:0xf bank_mask:0xf bound_ctrl:1
	v_mov_b32_dpp v23, v22 row_ror:1 row_mask:0xf bank_mask:0xf
	s_nop 0
	v_mov_b32_dpp v25, v24 row_ror:1 row_mask:0xf bank_mask:0xf
	s_and_saveexec_b64 s[4:5], s[0:1]
	v_add_f32_e32 v22, v22, v23
	v_add_f32_e32 v23, v24, v25
	ds_write2_b32 v20, v22, v23 offset0:160 offset1:176
	s_or_b64 exec, exec, s[4:5]
	ds_read2_b32 v[26:27], v21 offset0:192 offset1:208
	ds_read_b128 v[22:25], v82 offset:15360
	ds_read_b128 v[50:53], v82 offset:3072
	ds_read_b128 v[54:57], v82 offset:3328
	ds_read_b128 v[58:61], v82 offset:7168
	ds_read_b128 v[62:65], v82 offset:7424
	ds_read_b128 v[66:69], v82 offset:11264
	ds_read_b128 v[94:97], v82 offset:11520
	ds_read_b128 v[98:101], v82 offset:15616
	ds_read_b128 v[102:105], v82 offset:19456
	ds_read_b128 v[106:109], v82 offset:19712
	s_waitcnt lgkmcnt(9)
	v_pk_mul_f32 v[24:25], v[18:19], v[24:25]
	s_nop 0
	v_pk_fma_f32 v[22:23], v[16:17], v[22:23], v[24:25]
	s_nop 0
	v_add_f32_e32 v22, v22, v23
	s_nop 1
	v_add_f32_dpp v22, v22, v22 row_ror:8 row_mask:0xf bank_mask:0xf bound_ctrl:1
	s_nop 1
	v_add_f32_dpp v22, v22, v22 row_ror:4 row_mask:0xf bank_mask:0xf bound_ctrl:1
	s_nop 1
	v_add_f32_dpp v22, v22, v22 row_ror:2 row_mask:0xf bank_mask:0xf bound_ctrl:1
	s_nop 1
	v_add_f32_dpp v22, v22, v22 row_ror:1 row_mask:0xf bank_mask:0xf bound_ctrl:1
	s_waitcnt lgkmcnt(1)
	v_pk_mul_f32 v[24:25], v[102:103], v[22:23] op_sel_hi:[1,0]
	v_pk_mul_f32 v[22:23], v[104:105], v[22:23] op_sel_hi:[1,0]
	v_pk_fma_f32 v[24:25], v[26:27], v[58:59], v[24:25] op_sel_hi:[0,1,1] neg_lo:[0,0,1] neg_hi:[0,0,1]
	v_pk_fma_f32 v[22:23], v[26:27], v[60:61], v[22:23] op_sel_hi:[0,1,1] neg_lo:[0,0,1] neg_hi:[0,0,1]
	v_pk_fma_f32 v[18:19], v[18:19], v[68:69], v[22:23]
	v_pk_fma_f32 v[16:17], v[16:17], v[66:67], v[24:25]
	v_pk_mul_f32 v[22:23], v[52:53], v[18:19]
	v_mov_b32_e32 v24, v27
	v_pk_fma_f32 v[22:23], v[50:51], v[16:17], v[22:23]
	s_nop 0
	v_add_f32_e32 v25, v22, v23
	v_pk_mul_f32 v[22:23], v[100:101], v[18:19]
	s_nop 0
	v_pk_fma_f32 v[22:23], v[98:99], v[16:17], v[22:23]
	s_nop 0
	v_add_f32_e32 v22, v22, v23
	s_nop 1
	v_add_f32_dpp v22, v22, v22 row_ror:8 row_mask:0xf bank_mask:0xf bound_ctrl:1
	s_nop 1
	v_add_f32_dpp v22, v22, v22 row_ror:4 row_mask:0xf bank_mask:0xf bound_ctrl:1
	s_nop 1
	v_add_f32_dpp v22, v22, v22 row_ror:2 row_mask:0xf bank_mask:0xf bound_ctrl:1
	s_nop 1
	v_add_f32_dpp v22, v22, v22 row_ror:1 row_mask:0xf bank_mask:0xf bound_ctrl:1
	s_waitcnt lgkmcnt(0)
	v_pk_mul_f32 v[26:27], v[106:107], v[22:23] op_sel_hi:[1,0]
	v_pk_mul_f32 v[22:23], v[108:109], v[22:23] op_sel_hi:[1,0]
	v_pk_fma_f32 v[26:27], v[24:25], v[62:63], v[26:27] op_sel_hi:[0,1,1] neg_lo:[0,0,1] neg_hi:[0,0,1]
	v_pk_fma_f32 v[22:23], v[24:25], v[64:65], v[22:23] op_sel_hi:[0,1,1] neg_lo:[0,0,1] neg_hi:[0,0,1]
	v_pk_fma_f32 v[18:19], v[96:97], v[18:19], v[22:23]
	v_pk_fma_f32 v[16:17], v[94:95], v[16:17], v[26:27]
	v_pk_mul_f32 v[22:23], v[56:57], v[18:19]
	s_nop 0
	v_pk_fma_f32 v[22:23], v[54:55], v[16:17], v[22:23]
	s_nop 0
	v_add_f32_e32 v24, v22, v23
	v_add_f32_dpp v22, v25, v25 row_ror:8 row_mask:0xf bank_mask:0xf bound_ctrl:1
	v_mov_b32_e32 v23, v28
	v_add_f32_dpp v24, v24, v24 row_ror:8 row_mask:0xf bank_mask:0xf bound_ctrl:1
	v_add_f32_dpp v22, v22, v22 row_ror:4 row_mask:0xf bank_mask:0xf bound_ctrl:1
	v_mov_b32_e32 v25, v28
	v_add_f32_dpp v24, v24, v24 row_ror:4 row_mask:0xf bank_mask:0xf bound_ctrl:1
	v_add_f32_dpp v22, v22, v22 row_ror:2 row_mask:0xf bank_mask:0xf bound_ctrl:1
	s_nop 0
	v_add_f32_dpp v24, v24, v24 row_ror:2 row_mask:0xf bank_mask:0xf bound_ctrl:1
	v_mov_b32_dpp v23, v22 row_ror:1 row_mask:0xf bank_mask:0xf
	s_nop 0
	v_mov_b32_dpp v25, v24 row_ror:1 row_mask:0xf bank_mask:0xf
	s_and_saveexec_b64 s[4:5], s[0:1]
	v_add_f32_e32 v22, v22, v23
	v_add_f32_e32 v23, v24, v25
	ds_write2_b32 v20, v22, v23 offset0:192 offset1:208
	s_or_b64 exec, exec, s[4:5]
	ds_read2_b32 v[26:27], v21 offset0:224 offset1:240
	ds_read_b128 v[22:25], v82 offset:15872
	ds_read_b128 v[50:53], v82 offset:3584
	ds_read_b128 v[60:63], v82 offset:3840
	ds_read_b128 v[54:57], v82 offset:7680
	ds_read_b128 v[64:67], v82 offset:7936
	ds_read_b128 v[94:97], v82 offset:11776
	ds_read_b128 v[98:101], v82 offset:12032
	ds_read_b128 v[102:105], v82 offset:16128
	ds_read_b128 v[106:109], v82 offset:19968
	ds_read_b128 v[110:113], v82 offset:20224
	s_waitcnt lgkmcnt(9)
	v_pk_mul_f32 v[24:25], v[18:19], v[24:25]
	s_nop 0
	v_pk_fma_f32 v[22:23], v[16:17], v[22:23], v[24:25]
	s_nop 0
	v_add_f32_e32 v21, v22, v23
	s_nop 1
	v_add_f32_dpp v21, v21, v21 row_ror:8 row_mask:0xf bank_mask:0xf bound_ctrl:1
	s_nop 1
	v_add_f32_dpp v21, v21, v21 row_ror:4 row_mask:0xf bank_mask:0xf bound_ctrl:1
	s_nop 1
	v_add_f32_dpp v21, v21, v21 row_ror:2 row_mask:0xf bank_mask:0xf bound_ctrl:1
	s_nop 1
	v_add_f32_dpp v22, v21, v21 row_ror:1 row_mask:0xf bank_mask:0xf bound_ctrl:1
	s_waitcnt lgkmcnt(1)
	v_pk_mul_f32 v[24:25], v[106:107], v[22:23] op_sel_hi:[1,0]
	v_pk_mul_f32 v[22:23], v[108:109], v[22:23] op_sel_hi:[1,0]
	v_pk_fma_f32 v[24:25], v[26:27], v[54:55], v[24:25] op_sel_hi:[0,1,1] neg_lo:[0,0,1] neg_hi:[0,0,1]
	v_pk_fma_f32 v[22:23], v[26:27], v[56:57], v[22:23] op_sel_hi:[0,1,1] neg_lo:[0,0,1] neg_hi:[0,0,1]
	v_pk_fma_f32 v[18:19], v[18:19], v[96:97], v[22:23]
	v_pk_fma_f32 v[16:17], v[16:17], v[94:95], v[24:25]
	v_pk_mul_f32 v[22:23], v[52:53], v[18:19]
	v_mov_b32_e32 v24, v27
	v_pk_fma_f32 v[22:23], v[50:51], v[16:17], v[22:23]
	s_nop 0
	v_add_f32_e32 v21, v22, v23
	v_pk_mul_f32 v[22:23], v[104:105], v[18:19]
	s_nop 0
	v_pk_fma_f32 v[22:23], v[102:103], v[16:17], v[22:23]
	s_nop 0
	v_add_f32_e32 v22, v22, v23
	s_nop 1
	v_add_f32_dpp v22, v22, v22 row_ror:8 row_mask:0xf bank_mask:0xf bound_ctrl:1
	s_nop 1
	v_add_f32_dpp v22, v22, v22 row_ror:4 row_mask:0xf bank_mask:0xf bound_ctrl:1
	s_nop 1
	v_add_f32_dpp v22, v22, v22 row_ror:2 row_mask:0xf bank_mask:0xf bound_ctrl:1
	s_nop 1
	v_add_f32_dpp v22, v22, v22 row_ror:1 row_mask:0xf bank_mask:0xf bound_ctrl:1
	s_waitcnt lgkmcnt(0)
	v_pk_mul_f32 v[26:27], v[110:111], v[22:23] op_sel_hi:[1,0]
	v_pk_mul_f32 v[22:23], v[112:113], v[22:23] op_sel_hi:[1,0]
	v_pk_fma_f32 v[26:27], v[24:25], v[64:65], v[26:27] op_sel_hi:[0,1,1] neg_lo:[0,0,1] neg_hi:[0,0,1]
	v_pk_fma_f32 v[22:23], v[24:25], v[66:67], v[22:23] op_sel_hi:[0,1,1] neg_lo:[0,0,1] neg_hi:[0,0,1]
	v_pk_fma_f32 v[58:59], v[100:101], v[18:19], v[22:23]
	v_pk_fma_f32 v[56:57], v[98:99], v[16:17], v[26:27]
	v_pk_mul_f32 v[16:17], v[62:63], v[58:59]
	v_mov_b32_e32 v19, v28
	v_pk_fma_f32 v[16:17], v[60:61], v[56:57], v[16:17]
	s_nop 0
	v_add_f32_e32 v18, v16, v17
	v_add_f32_dpp v16, v21, v21 row_ror:8 row_mask:0xf bank_mask:0xf bound_ctrl:1
	v_mov_b32_e32 v17, v28
	v_add_f32_dpp v18, v18, v18 row_ror:8 row_mask:0xf bank_mask:0xf bound_ctrl:1
	v_add_f32_dpp v16, v16, v16 row_ror:4 row_mask:0xf bank_mask:0xf bound_ctrl:1
	s_nop 0
	v_add_f32_dpp v18, v18, v18 row_ror:4 row_mask:0xf bank_mask:0xf bound_ctrl:1
	v_add_f32_dpp v16, v16, v16 row_ror:2 row_mask:0xf bank_mask:0xf bound_ctrl:1
	s_nop 0
	v_add_f32_dpp v18, v18, v18 row_ror:2 row_mask:0xf bank_mask:0xf bound_ctrl:1
	v_mov_b32_dpp v17, v16 row_ror:1 row_mask:0xf bank_mask:0xf
	s_nop 0
	v_mov_b32_dpp v19, v18 row_ror:1 row_mask:0xf bank_mask:0xf
	s_and_saveexec_b64 s[4:5], s[0:1]
	v_add_f32_e32 v16, v16, v17
	v_add_f32_e32 v17, v18, v19
	ds_write2_b32 v20, v16, v17 offset0:224 offset1:240
	s_or_b64 exec, exec, s[4:5]
	s_lshl_b32 s86, s9, 1
	s_add_u32 s4, s40, s86
	s_addc_u32 s5, s41, 0
	s_lshl_b32 s10, s97, 1
	s_add_u32 s4, s4, s10
	s_addc_u32 s5, s5, 0
	v_lshlrev_b32_e32 v50, 1, v79
	v_mov_b32_e32 v51, v28
	v_lshl_add_u64 v[52:53], s[4:5], 0, v[50:51]
	s_add_u32 s4, s44, s86
	s_addc_u32 s5, s45, 0
	v_sub_u32_e32 v93, 0x800, v83
	v_lshl_add_u64 v[54:55], v[34:35], 1, s[4:5]
	s_mov_b32 s13, 0
	s_mov_b32 s11, 0
	global_load_dword v253, v28, s[40:41]

.LBB0_427:
	s_or_b64 exec, exec, s[4:5]
	v_add_u32_e32 v16, s11, v83
	s_bitcmp1_b32 s13, 0
	s_cselect_b32 s13, 0x5800, 0
	v_add_u32_e32 v250, s13, v31
	v_add_u32_e32 v172, s11, v30
	v_ashrrev_i32_e32 v173, 31, v172
	v_lshlrev_b64 v[172:173], 11, v[172:173]
	v_lshl_add_u64 v[172:173], v[52:53], 0, v[172:173]
	v_add_u32_e32 v17, 32, v16
	v_cmp_gt_i32_e32 vcc, s94, v17
	s_and_saveexec_b64 s[4:5], vcc
	s_cbranch_execz .LBB0_433
	v_add3_u32 v16, v30, s11, 32
	v_mov_b64_e32 v[18:19], s[42:43]
	v_mad_i64_i32 v[22:23], s[34:35], v16, s7, v[18:19]
	v_lshl_add_u64 v[20:21], v[22:23], 0, s[86:87]
	v_lshl_add_u64 v[18:19], v[34:35], 1, v[20:21]
	v_add_co_u32_e32 v24, vcc, 0x1000, v18
	v_lshl_add_u64 v[22:23], v[38:39], 1, v[22:23]
	s_nop 0
	v_addc_co_u32_e32 v25, vcc, 0, v19, vcc
	global_load_dwordx2 v[40:41], v[18:19], off offset:3584
	global_load_dwordx2 v[36:37], v[24:25], off offset:128
	global_load_ushort v85, v[22:23], off
	v_mov_b32_e32 v29, v28
	v_cmp_lt_i32_e32 vcc, 0, v17
	s_waitcnt vmcnt(6)
	v_mov_b32_e32 v86, 0
	s_waitcnt vmcnt(5)
	v_mov_b64_e32 v[42:43], v[28:29]
	v_mov_b64_e32 v[44:45], v[28:29]
	s_and_saveexec_b64 s[88:89], vcc
	s_cbranch_execz .LBB0_432
	v_add_co_u32_e32 v22, vcc, 0xfffff000, v18
	s_mov_b32 s11, s87
	s_nop 0
	v_addc_co_u32_e32 v23, vcc, -1, v19, vcc
	v_lshl_add_u64 v[20:21], v[20:21], 0, s[10:11]
	v_mov_b32_e32 v51, v28
	v_lshl_add_u64 v[20:21], v[20:21], 0, v[50:51]
	global_load_dwordx2 v[44:45], v[22:23], off offset:-32
	global_load_ushort v86, v[20:21], off offset:-2976
	global_load_dwordx2 v[42:43], v[18:19], off offset:-3488

.LBB0_433:
	s_or_b64 exec, exec, s[4:5]
	s_waitcnt lgkmcnt(0)
	s_barrier
	ds_read_b32 v250, v250 offset:21504
	v_lshl_add_u32 v17, v34, 2, s84
	v_add3_u32 v18, s84, v91, v92
	v_add_u32_e32 v25, 0x5000, v18
	v_bfe_u32 v19, v34, 2, 2
	ds_read2_b32 v[236:237], v25 offset0:0 offset1:16
	ds_read_b128 v[164:167], v17 offset:12288
	ds_read_b128 v[156:159], v17 offset:4096
	ds_read_b128 v[168:171], v17 offset:16384
	ds_read_b128 v[160:163], v17 offset:8192
	ds_read_b128 v[152:155], v17
	ds_read_b128 v[188:191], v17 offset:12544
	ds_read_b128 v[180:183], v17 offset:4352
	ds_read_b128 v[192:195], v17 offset:16640
	ds_read_b128 v[184:187], v17 offset:8448
	ds_read_b128 v[176:179], v17 offset:256
	s_waitcnt lgkmcnt(0)
	v_cvt_f16_f32_e32 v250, v250
	global_store_short v[172:173], v250, off offset:1024
	v_mul_f32_e32 v16, v164, v56
	v_fmac_f32_e32 v16, v165, v57
	v_fmac_f32_e32 v16, v166, v58
	v_fmac_f32_e32 v16, v167, v59
	v_mul_f32_e32 v20, v156, v236
	v_mul_f32_e32 v21, v157, v236
	v_add_f32_dpp v16, v16, v16 row_ror:8 row_mask:0xf bank_mask:0xf bound_ctrl:1
	v_mul_f32_e32 v22, v158, v236
	v_mul_f32_e32 v23, v159, v236
	v_add_f32_dpp v16, v16, v16 row_ror:4 row_mask:0xf bank_mask:0xf bound_ctrl:1
	ds_read2_b32 v[238:239], v25 offset0:32 offset1:48
	ds_read_b128 v[208:211], v17 offset:12800
	v_add_f32_dpp v16, v16, v16 row_ror:2 row_mask:0xf bank_mask:0xf bound_ctrl:1
	ds_read_b128 v[204:207], v17 offset:8704
	ds_read_b128 v[200:203], v17 offset:4608
	ds_read_b128 v[212:215], v17 offset:16896
	v_add_f32_dpp v16, v16, v16 row_ror:1 row_mask:0xf bank_mask:0xf bound_ctrl:1
	v_fma_f32 v20, -v168, v16, v20
	v_fma_f32 v21, -v169, v16, v21
	ds_read_b128 v[196:199], v17 offset:512
	v_fma_f32 v56, v160, v56, v20
	v_fma_f32 v22, -v170, v16, v22
	v_fma_f32 v57, v161, v57, v21
	v_fma_f32 v23, -v171, v16, v23
	v_fma_f32 v58, v162, v58, v22
	ds_read_b128 v[228:231], v17 offset:13056
	v_fma_f32 v59, v163, v59, v23
	v_mul_f32_e32 v16, v188, v56
	v_fmac_f32_e32 v16, v189, v57
	v_fmac_f32_e32 v16, v190, v58
	v_fmac_f32_e32 v16, v191, v59
	ds_read_b128 v[220:223], v17 offset:4864
	v_mul_f32_e32 v20, v180, v237
	v_mul_f32_e32 v21, v181, v237
	v_add_f32_dpp v16, v16, v16 row_ror:8 row_mask:0xf bank_mask:0xf bound_ctrl:1
	v_mul_f32_e32 v22, v182, v237
	v_mul_f32_e32 v23, v183, v237
	ds_read_b128 v[232:235], v17 offset:17152
	v_add_f32_dpp v16, v16, v16 row_ror:4 row_mask:0xf bank_mask:0xf bound_ctrl:1
	v_mul_f32_e32 v240, v152, v56
	v_fmac_f32_e32 v240, v153, v57
	v_add_f32_dpp v16, v16, v16 row_ror:2 row_mask:0xf bank_mask:0xf bound_ctrl:1
	v_fmac_f32_e32 v240, v154, v58
	ds_read_b128 v[224:227], v17 offset:8960
	v_fmac_f32_e32 v240, v155, v59
	v_add_f32_dpp v16, v16, v16 row_ror:1 row_mask:0xf bank_mask:0xf bound_ctrl:1
	v_fma_f32 v20, -v192, v16, v20
	v_fma_f32 v21, -v193, v16, v21
	v_fma_f32 v56, v184, v56, v20
	ds_read_b128 v[216:219], v17 offset:768
	v_fma_f32 v22, -v194, v16, v22
	v_fma_f32 v57, v185, v57, v21
	v_fma_f32 v23, -v195, v16, v23
	v_fma_f32 v58, v186, v58, v22
	v_fma_f32 v59, v187, v59, v23
	s_waitcnt lgkmcnt(0)
	v_mul_f32_e32 v16, v208, v56
	v_fmac_f32_e32 v16, v209, v57
	v_fmac_f32_e32 v16, v210, v58
	v_fmac_f32_e32 v16, v211, v59
	v_mul_f32_e32 v20, v200, v238
	v_mul_f32_e32 v21, v201, v238
	v_add_f32_dpp v16, v16, v16 row_ror:8 row_mask:0xf bank_mask:0xf bound_ctrl:1
	v_mul_f32_e32 v22, v202, v238
	v_mul_f32_e32 v23, v203, v238
	v_add_f32_dpp v16, v16, v16 row_ror:4 row_mask:0xf bank_mask:0xf bound_ctrl:1
	v_mul_f32_e32 v241, v176, v56
	v_fmac_f32_e32 v241, v177, v57
	v_add_f32_dpp v16, v16, v16 row_ror:2 row_mask:0xf bank_mask:0xf bound_ctrl:1
	ds_read2_b32 v[236:237], v25 offset0:64 offset1:80
	v_fmac_f32_e32 v241, v178, v58
	v_fmac_f32_e32 v241, v179, v59
	v_add_f32_dpp v16, v16, v16 row_ror:1 row_mask:0xf bank_mask:0xf bound_ctrl:1
	ds_read_b128 v[164:167], v17 offset:13312
	v_fma_f32 v20, -v212, v16, v20
	v_fma_f32 v21, -v213, v16, v21
	v_fma_f32 v56, v204, v56, v20
	ds_read_b128 v[156:159], v17 offset:5120
	v_fma_f32 v22, -v214, v16, v22
	v_fma_f32 v57, v205, v57, v21
	v_fma_f32 v23, -v215, v16, v23
	ds_read_b128 v[168:171], v17 offset:17408
	v_fma_f32 v58, v206, v58, v22
	v_fma_f32 v59, v207, v59, v23
	v_mul_f32_e32 v16, v228, v56
	v_fmac_f32_e32 v16, v229, v57
	ds_read_b128 v[160:163], v17 offset:9216
	v_fmac_f32_e32 v16, v230, v58
	v_fmac_f32_e32 v16, v231, v59
	v_mul_f32_e32 v20, v220, v239
	ds_read_b128 v[152:155], v17 offset:1024
	v_mul_f32_e32 v21, v221, v239
	v_add_f32_dpp v16, v16, v16 row_ror:8 row_mask:0xf bank_mask:0xf bound_ctrl:1
	v_mul_f32_e32 v22, v222, v239
	ds_read_b128 v[188:191], v17 offset:13568
	v_mul_f32_e32 v23, v223, v239
	v_add_f32_dpp v16, v16, v16 row_ror:4 row_mask:0xf bank_mask:0xf bound_ctrl:1
	v_mul_f32_e32 v242, v196, v56
	ds_read_b128 v[180:183], v17 offset:5376
	v_fmac_f32_e32 v242, v197, v57
	v_add_f32_dpp v16, v16, v16 row_ror:2 row_mask:0xf bank_mask:0xf bound_ctrl:1
	v_fmac_f32_e32 v242, v198, v58
	v_fmac_f32_e32 v242, v199, v59
	ds_read_b128 v[192:195], v17 offset:17664
	v_add_f32_dpp v16, v16, v16 row_ror:1 row_mask:0xf bank_mask:0xf bound_ctrl:1
	v_fma_f32 v20, -v232, v16, v20
	v_fma_f32 v21, -v233, v16, v21
	ds_read_b128 v[184:187], v17 offset:9472
	v_fma_f32 v56, v224, v56, v20
	v_fma_f32 v22, -v234, v16, v22
	v_fma_f32 v57, v225, v57, v21
	ds_read_b128 v[176:179], v17 offset:1280
	v_fma_f32 v23, -v235, v16, v23
	v_fma_f32 v58, v226, v58, v22
	v_fma_f32 v59, v227, v59, v23
	s_waitcnt lgkmcnt(0)
	v_mul_f32_e32 v16, v164, v56
	v_fmac_f32_e32 v16, v165, v57
	v_fmac_f32_e32 v16, v166, v58
	v_fmac_f32_e32 v16, v167, v59
	v_mul_f32_e32 v20, v156, v236
	v_mul_f32_e32 v21, v157, v236
	v_add_f32_dpp v16, v16, v16 row_ror:8 row_mask:0xf bank_mask:0xf bound_ctrl:1
	v_mul_f32_e32 v22, v158, v236
	v_mul_f32_e32 v23, v159, v236
	v_add_f32_dpp v16, v16, v16 row_ror:4 row_mask:0xf bank_mask:0xf bound_ctrl:1
	v_mul_f32_e32 v243, v216, v56
	v_fmac_f32_e32 v243, v217, v57
	v_add_f32_dpp v16, v16, v16 row_ror:2 row_mask:0xf bank_mask:0xf bound_ctrl:1
	ds_read2_b32 v[238:239], v25 offset0:96 offset1:112
	v_fmac_f32_e32 v243, v218, v58
	v_fmac_f32_e32 v243, v219, v59
	v_add_f32_dpp v16, v16, v16 row_ror:1 row_mask:0xf bank_mask:0xf bound_ctrl:1
	ds_read_b128 v[208:211], v17 offset:13824
	v_fma_f32 v20, -v168, v16, v20
	v_fma_f32 v21, -v169, v16, v21
	v_fma_f32 v56, v160, v56, v20
	ds_read_b128 v[200:203], v17 offset:5632
	v_fma_f32 v22, -v170, v16, v22
	v_fma_f32 v57, v161, v57, v21
	v_fma_f32 v23, -v171, v16, v23
	ds_read_b128 v[212:215], v17 offset:17920
	v_fma_f32 v58, v162, v58, v22
	v_fma_f32 v59, v163, v59, v23
	v_mul_f32_e32 v16, v188, v56
	v_fmac_f32_e32 v16, v189, v57
	ds_read_b128 v[204:207], v17 offset:9728
	v_fmac_f32_e32 v16, v190, v58
	v_fmac_f32_e32 v16, v191, v59
	v_mul_f32_e32 v20, v180, v237
	ds_read_b128 v[196:199], v17 offset:1536
	v_mul_f32_e32 v21, v181, v237
	v_add_f32_dpp v16, v16, v16 row_ror:8 row_mask:0xf bank_mask:0xf bound_ctrl:1
	v_mul_f32_e32 v22, v182, v237
	ds_read_b128 v[228:231], v17 offset:14080
	v_mul_f32_e32 v23, v183, v237
	v_add_f32_dpp v16, v16, v16 row_ror:4 row_mask:0xf bank_mask:0xf bound_ctrl:1
	v_mul_f32_e32 v244, v152, v56
	ds_read_b128 v[220:223], v17 offset:5888
	v_fmac_f32_e32 v244, v153, v57
	v_add_f32_dpp v16, v16, v16 row_ror:2 row_mask:0xf bank_mask:0xf bound_ctrl:1
	v_fmac_f32_e32 v244, v154, v58
	v_fmac_f32_e32 v244, v155, v59
	ds_read_b128 v[232:235], v17 offset:18176
	v_add_f32_dpp v16, v16, v16 row_ror:1 row_mask:0xf bank_mask:0xf bound_ctrl:1
	v_fma_f32 v20, -v192, v16, v20
	v_fma_f32 v21, -v193, v16, v21
	ds_read_b128 v[224:227], v17 offset:9984
	v_fma_f32 v56, v184, v56, v20
	v_fma_f32 v22, -v194, v16, v22
	v_fma_f32 v57, v185, v57, v21
	ds_read_b128 v[216:219], v17 offset:1792
	v_fma_f32 v23, -v195, v16, v23
	v_fma_f32 v58, v186, v58, v22
	v_fma_f32 v59, v187, v59, v23
	s_waitcnt lgkmcnt(0)
	v_mul_f32_e32 v16, v208, v56
	v_fmac_f32_e32 v16, v209, v57
	v_fmac_f32_e32 v16, v210, v58
	v_fmac_f32_e32 v16, v211, v59
	v_mul_f32_e32 v20, v200, v238
	v_mul_f32_e32 v21, v201, v238
	v_add_f32_dpp v16, v16, v16 row_ror:8 row_mask:0xf bank_mask:0xf bound_ctrl:1
	v_mul_f32_e32 v22, v202, v238
	v_mul_f32_e32 v23, v203, v238
	v_add_f32_dpp v16, v16, v16 row_ror:4 row_mask:0xf bank_mask:0xf bound_ctrl:1
	v_mul_f32_e32 v245, v176, v56
	v_fmac_f32_e32 v245, v177, v57
	v_add_f32_dpp v16, v16, v16 row_ror:2 row_mask:0xf bank_mask:0xf bound_ctrl:1
	ds_read2_b32 v[236:237], v25 offset0:128 offset1:144
	v_fmac_f32_e32 v245, v178, v58
	v_fmac_f32_e32 v245, v179, v59
	v_add_f32_dpp v16, v16, v16 row_ror:1 row_mask:0xf bank_mask:0xf bound_ctrl:1
	ds_read_b128 v[164:167], v17 offset:14336
	v_fma_f32 v20, -v212, v16, v20
	v_fma_f32 v21, -v213, v16, v21
	v_fma_f32 v56, v204, v56, v20
	ds_read_b128 v[156:159], v17 offset:6144
	v_fma_f32 v22, -v214, v16, v22
	v_fma_f32 v57, v205, v57, v21
	v_fma_f32 v23, -v215, v16, v23
	ds_read_b128 v[168:171], v17 offset:18432
	v_fma_f32 v58, v206, v58, v22
	v_fma_f32 v59, v207, v59, v23
	v_mul_f32_e32 v16, v228, v56
	v_fmac_f32_e32 v16, v229, v57
	ds_read_b128 v[160:163], v17 offset:10240
	v_fmac_f32_e32 v16, v230, v58
	v_fmac_f32_e32 v16, v231, v59
	v_mul_f32_e32 v20, v220, v239
	ds_read_b128 v[152:155], v17 offset:2048
	v_mul_f32_e32 v21, v221, v239
	v_add_f32_dpp v16, v16, v16 row_ror:8 row_mask:0xf bank_mask:0xf bound_ctrl:1
	v_mul_f32_e32 v22, v222, v239
	ds_read_b128 v[188:191], v17 offset:14592
	v_mul_f32_e32 v23, v223, v239
	v_add_f32_dpp v16, v16, v16 row_ror:4 row_mask:0xf bank_mask:0xf bound_ctrl:1
	v_mul_f32_e32 v246, v196, v56
	ds_read_b128 v[180:183], v17 offset:6400
	v_fmac_f32_e32 v246, v197, v57
	v_add_f32_dpp v16, v16, v16 row_ror:2 row_mask:0xf bank_mask:0xf bound_ctrl:1
	v_fmac_f32_e32 v246, v198, v58
	v_fmac_f32_e32 v246, v199, v59
	ds_read_b128 v[192:195], v17 offset:18688
	v_add_f32_dpp v16, v16, v16 row_ror:1 row_mask:0xf bank_mask:0xf bound_ctrl:1
	v_fma_f32 v20, -v232, v16, v20
	v_fma_f32 v21, -v233, v16, v21
	ds_read_b128 v[184:187], v17 offset:10496
	v_fma_f32 v56, v224, v56, v20
	v_fma_f32 v22, -v234, v16, v22
	v_fma_f32 v57, v225, v57, v21
	ds_read_b128 v[176:179], v17 offset:2304
	v_fma_f32 v23, -v235, v16, v23
	v_fma_f32 v58, v226, v58, v22
	v_fma_f32 v59, v227, v59, v23
	s_waitcnt lgkmcnt(0)
	v_mul_f32_e32 v16, v164, v56
	v_fmac_f32_e32 v16, v165, v57
	v_fmac_f32_e32 v16, v166, v58
	v_fmac_f32_e32 v16, v167, v59
	v_mul_f32_e32 v20, v156, v236
	v_mul_f32_e32 v21, v157, v236
	v_add_f32_dpp v16, v16, v16 row_ror:8 row_mask:0xf bank_mask:0xf bound_ctrl:1
	v_mul_f32_e32 v22, v158, v236
	v_mul_f32_e32 v23, v159, v236
	v_add_f32_dpp v16, v16, v16 row_ror:4 row_mask:0xf bank_mask:0xf bound_ctrl:1
	v_mul_f32_e32 v247, v216, v56
	v_fmac_f32_e32 v247, v217, v57
	v_add_f32_dpp v16, v16, v16 row_ror:2 row_mask:0xf bank_mask:0xf bound_ctrl:1
	ds_read2_b32 v[238:239], v25 offset0:160 offset1:176
	v_fmac_f32_e32 v247, v218, v58
	v_fmac_f32_e32 v247, v219, v59
	v_add_f32_dpp v16, v16, v16 row_ror:1 row_mask:0xf bank_mask:0xf bound_ctrl:1
	ds_read_b128 v[208:211], v17 offset:14848
	v_fma_f32 v20, -v168, v16, v20
	v_fma_f32 v21, -v169, v16, v21
	v_fma_f32 v56, v160, v56, v20
	ds_read_b128 v[200:203], v17 offset:6656
	v_fma_f32 v22, -v170, v16, v22
	v_fma_f32 v57, v161, v57, v21
	v_fma_f32 v23, -v171, v16, v23
	ds_read_b128 v[212:215], v17 offset:18944
	v_fma_f32 v58, v162, v58, v22
	v_fma_f32 v59, v163, v59, v23
	v_mul_f32_e32 v16, v188, v56
	v_fmac_f32_e32 v16, v189, v57
	ds_read_b128 v[204:207], v17 offset:10752
	v_fmac_f32_e32 v16, v190, v58
	v_fmac_f32_e32 v16, v191, v59
	v_mul_f32_e32 v20, v180, v237
	ds_read_b128 v[196:199], v17 offset:2560
	v_mul_f32_e32 v21, v181, v237
	v_add_f32_dpp v16, v16, v16 row_ror:8 row_mask:0xf bank_mask:0xf bound_ctrl:1
	v_mul_f32_e32 v22, v182, v237
	ds_read_b128 v[228:231], v17 offset:15104
	v_mul_f32_e32 v23, v183, v237
	v_add_f32_dpp v16, v16, v16 row_ror:4 row_mask:0xf bank_mask:0xf bound_ctrl:1
	v_mul_f32_e32 v248, v152, v56
	ds_read_b128 v[220:223], v17 offset:6912
	v_fmac_f32_e32 v248, v153, v57
	v_add_f32_dpp v16, v16, v16 row_ror:2 row_mask:0xf bank_mask:0xf bound_ctrl:1
	v_fmac_f32_e32 v248, v154, v58
	v_fmac_f32_e32 v248, v155, v59
	ds_read_b128 v[232:235], v17 offset:19200
	v_add_f32_dpp v16, v16, v16 row_ror:1 row_mask:0xf bank_mask:0xf bound_ctrl:1
	v_fma_f32 v20, -v192, v16, v20
	v_fma_f32 v21, -v193, v16, v21
	ds_read_b128 v[224:227], v17 offset:11008
	v_fma_f32 v56, v184, v56, v20
	v_fma_f32 v22, -v194, v16, v22
	v_fma_f32 v57, v185, v57, v21
	ds_read_b128 v[216:219], v17 offset:2816
	v_fma_f32 v23, -v195, v16, v23
	v_fma_f32 v58, v186, v58, v22
	v_fma_f32 v59, v187, v59, v23
	s_waitcnt lgkmcnt(0)
	v_mul_f32_e32 v16, v208, v56
	v_fmac_f32_e32 v16, v209, v57
	v_fmac_f32_e32 v16, v210, v58
	v_fmac_f32_e32 v16, v211, v59
	v_mul_f32_e32 v20, v200, v238
	v_mul_f32_e32 v21, v201, v238
	v_add_f32_dpp v16, v16, v16 row_ror:8 row_mask:0xf bank_mask:0xf bound_ctrl:1
	v_mul_f32_e32 v22, v202, v238
	v_mul_f32_e32 v23, v203, v238
	v_add_f32_dpp v16, v16, v16 row_ror:4 row_mask:0xf bank_mask:0xf bound_ctrl:1
	v_mul_f32_e32 v249, v176, v56
	v_fmac_f32_e32 v249, v177, v57
	v_add_f32_dpp v16, v16, v16 row_ror:2 row_mask:0xf bank_mask:0xf bound_ctrl:1
	ds_read2_b32 v[236:237], v25 offset0:192 offset1:208
	v_fmac_f32_e32 v249, v178, v58
	v_fmac_f32_e32 v249, v179, v59
	v_add_f32_dpp v16, v16, v16 row_ror:1 row_mask:0xf bank_mask:0xf bound_ctrl:1
	ds_read_b128 v[164:167], v17 offset:15360
	v_fma_f32 v20, -v212, v16, v20
	v_fma_f32 v21, -v213, v16, v21
	v_fma_f32 v56, v204, v56, v20
	ds_read_b128 v[156:159], v17 offset:7168
	v_fma_f32 v22, -v214, v16, v22
	v_fma_f32 v57, v205, v57, v21
	v_fma_f32 v23, -v215, v16, v23
	ds_read_b128 v[168:171], v17 offset:19456
	v_fma_f32 v58, v206, v58, v22
	v_fma_f32 v59, v207, v59, v23
	v_mul_f32_e32 v16, v228, v56
	v_fmac_f32_e32 v16, v229, v57
	ds_read_b128 v[160:163], v17 offset:11264
	v_fmac_f32_e32 v16, v230, v58
	v_fmac_f32_e32 v16, v231, v59
	v_mul_f32_e32 v20, v220, v239
	ds_read_b128 v[152:155], v17 offset:3072
	v_mul_f32_e32 v21, v221, v239
	v_add_f32_dpp v16, v16, v16 row_ror:8 row_mask:0xf bank_mask:0xf bound_ctrl:1
	v_mul_f32_e32 v22, v222, v239
	ds_read_b128 v[188:191], v17 offset:15616
	v_mul_f32_e32 v23, v223, v239
	v_add_f32_dpp v16, v16, v16 row_ror:4 row_mask:0xf bank_mask:0xf bound_ctrl:1
	v_mul_f32_e32 v150, v196, v56
	ds_read_b128 v[180:183], v17 offset:7424
	v_fmac_f32_e32 v150, v197, v57
	v_add_f32_dpp v16, v16, v16 row_ror:2 row_mask:0xf bank_mask:0xf bound_ctrl:1
	v_fmac_f32_e32 v150, v198, v58
	v_fmac_f32_e32 v150, v199, v59
	ds_read_b128 v[192:195], v17 offset:19712
	v_add_f32_dpp v16, v16, v16 row_ror:1 row_mask:0xf bank_mask:0xf bound_ctrl:1
	v_fma_f32 v20, -v232, v16, v20
	v_fma_f32 v21, -v233, v16, v21
	ds_read_b128 v[184:187], v17 offset:11520
	v_fma_f32 v56, v224, v56, v20
	v_fma_f32 v22, -v234, v16, v22
	v_fma_f32 v57, v225, v57, v21
	ds_read_b128 v[176:179], v17 offset:3328
	v_fma_f32 v23, -v235, v16, v23
	v_fma_f32 v58, v226, v58, v22
	v_fma_f32 v59, v227, v59, v23
	s_waitcnt lgkmcnt(0)
	v_mul_f32_e32 v16, v164, v56
	v_fmac_f32_e32 v16, v165, v57
	v_fmac_f32_e32 v16, v166, v58
	v_fmac_f32_e32 v16, v167, v59
	v_mul_f32_e32 v20, v156, v236
	v_mul_f32_e32 v21, v157, v236
	v_add_f32_dpp v16, v16, v16 row_ror:8 row_mask:0xf bank_mask:0xf bound_ctrl:1
	v_mul_f32_e32 v22, v158, v236
	v_mul_f32_e32 v23, v159, v236
	v_add_f32_dpp v16, v16, v16 row_ror:4 row_mask:0xf bank_mask:0xf bound_ctrl:1
	v_mul_f32_e32 v151, v216, v56
	v_fmac_f32_e32 v151, v217, v57
	v_add_f32_dpp v16, v16, v16 row_ror:2 row_mask:0xf bank_mask:0xf bound_ctrl:1
	ds_read2_b32 v[238:239], v25 offset0:224 offset1:240
	v_fmac_f32_e32 v151, v218, v58
	v_fmac_f32_e32 v151, v219, v59
	v_add_f32_dpp v16, v16, v16 row_ror:1 row_mask:0xf bank_mask:0xf bound_ctrl:1
	ds_read_b128 v[208:211], v17 offset:15872
	v_fma_f32 v20, -v168, v16, v20
	v_fma_f32 v21, -v169, v16, v21
	v_fma_f32 v56, v160, v56, v20
	ds_read_b128 v[200:203], v17 offset:7680
	v_fma_f32 v22, -v170, v16, v22
	v_fma_f32 v57, v161, v57, v21
	v_fma_f32 v23, -v171, v16, v23
	ds_read_b128 v[212:215], v17 offset:19968
	v_fma_f32 v58, v162, v58, v22
	v_fma_f32 v59, v163, v59, v23
	v_mul_f32_e32 v16, v188, v56
	v_fmac_f32_e32 v16, v189, v57
	ds_read_b128 v[204:207], v17 offset:11776
	v_fmac_f32_e32 v16, v190, v58
	v_fmac_f32_e32 v16, v191, v59
	v_mul_f32_e32 v20, v180, v237
	ds_read_b128 v[196:199], v17 offset:3584
	v_mul_f32_e32 v21, v181, v237
	v_add_f32_dpp v16, v16, v16 row_ror:8 row_mask:0xf bank_mask:0xf bound_ctrl:1
	v_mul_f32_e32 v22, v182, v237
	ds_read_b128 v[228:231], v17 offset:16128
	v_mul_f32_e32 v23, v183, v237
	v_add_f32_dpp v16, v16, v16 row_ror:4 row_mask:0xf bank_mask:0xf bound_ctrl:1
	v_mul_f32_e32 v26, v152, v56
	ds_read_b128 v[220:223], v17 offset:7936
	v_fmac_f32_e32 v26, v153, v57
	v_add_f32_dpp v16, v16, v16 row_ror:2 row_mask:0xf bank_mask:0xf bound_ctrl:1
	v_fmac_f32_e32 v26, v154, v58
	v_fmac_f32_e32 v26, v155, v59
	ds_read_b128 v[232:235], v17 offset:20224
	v_add_f32_dpp v16, v16, v16 row_ror:1 row_mask:0xf bank_mask:0xf bound_ctrl:1
	v_fma_f32 v20, -v192, v16, v20
	v_fma_f32 v21, -v193, v16, v21
	ds_read_b128 v[224:227], v17 offset:12032
	v_fma_f32 v56, v184, v56, v20
	v_fma_f32 v22, -v194, v16, v22
	v_fma_f32 v57, v185, v57, v21
	ds_read_b128 v[216:219], v17 offset:3840
	v_fma_f32 v23, -v195, v16, v23
	v_fma_f32 v58, v186, v58, v22
	v_fma_f32 v59, v187, v59, v23
	s_waitcnt lgkmcnt(0)
	v_mul_f32_e32 v16, v208, v56
	v_fmac_f32_e32 v16, v209, v57
	v_fmac_f32_e32 v16, v210, v58
	v_fmac_f32_e32 v16, v211, v59
	v_mul_f32_e32 v20, v200, v238
	v_mul_f32_e32 v21, v201, v238
	v_add_f32_dpp v16, v16, v16 row_ror:8 row_mask:0xf bank_mask:0xf bound_ctrl:1
	v_mul_f32_e32 v22, v202, v238
	v_mul_f32_e32 v23, v203, v238
	v_add_f32_dpp v16, v16, v16 row_ror:4 row_mask:0xf bank_mask:0xf bound_ctrl:1
	v_mul_f32_e32 v27, v176, v56
	v_fmac_f32_e32 v27, v177, v57
	v_add_f32_dpp v16, v16, v16 row_ror:2 row_mask:0xf bank_mask:0xf bound_ctrl:1
	v_fmac_f32_e32 v27, v178, v58
	v_fmac_f32_e32 v27, v179, v59
	v_add_f32_dpp v16, v16, v16 row_ror:1 row_mask:0xf bank_mask:0xf bound_ctrl:1
	v_fma_f32 v20, -v212, v16, v20
	v_fma_f32 v21, -v213, v16, v21
	v_fma_f32 v56, v204, v56, v20
	v_fma_f32 v22, -v214, v16, v22
	v_fma_f32 v57, v205, v57, v21
	v_fma_f32 v23, -v215, v16, v23
	v_fma_f32 v58, v206, v58, v22
	v_fma_f32 v59, v207, v59, v23
	v_mul_f32_e32 v16, v228, v56
	v_fmac_f32_e32 v16, v229, v57
	v_fmac_f32_e32 v16, v230, v58
	v_fmac_f32_e32 v16, v231, v59
	v_mul_f32_e32 v20, v220, v239
	v_mul_f32_e32 v21, v221, v239
	v_add_f32_dpp v16, v16, v16 row_ror:8 row_mask:0xf bank_mask:0xf bound_ctrl:1
	v_mul_f32_e32 v22, v222, v239
	v_mul_f32_e32 v23, v223, v239
	v_add_f32_dpp v16, v16, v16 row_ror:4 row_mask:0xf bank_mask:0xf bound_ctrl:1
	v_mul_f32_e32 v62, v196, v56
	v_fmac_f32_e32 v62, v197, v57
	v_add_f32_dpp v16, v16, v16 row_ror:2 row_mask:0xf bank_mask:0xf bound_ctrl:1
	v_fmac_f32_e32 v62, v198, v58
	v_fmac_f32_e32 v62, v199, v59
	v_add_f32_dpp v16, v16, v16 row_ror:1 row_mask:0xf bank_mask:0xf bound_ctrl:1
	v_fma_f32 v20, -v232, v16, v20
	v_fma_f32 v21, -v233, v16, v21
	v_fma_f32 v56, v224, v56, v20
	v_fma_f32 v22, -v234, v16, v22
	v_fma_f32 v57, v225, v57, v21
	v_fma_f32 v23, -v235, v16, v23
	v_fma_f32 v58, v226, v58, v22
	v_fma_f32 v59, v227, v59, v23
	v_mul_f32_e32 v63, v216, v56
	v_fmac_f32_e32 v63, v217, v57
	v_fmac_f32_e32 v63, v218, v58
	v_fmac_f32_e32 v63, v219, v59
	v_add_f32_dpp v240, v240, v240 row_ror:8 row_mask:0xf bank_mask:0x3
	v_add_f32_dpp v241, v241, v241 row_ror:8 row_mask:0xf bank_mask:0x3
	v_add_f32_dpp v242, v242, v242 row_ror:8 row_mask:0xf bank_mask:0x3
	v_add_f32_dpp v243, v243, v243 row_ror:8 row_mask:0xf bank_mask:0x3
	v_add_f32_dpp v244, v244, v244 row_ror:8 row_mask:0xf bank_mask:0x3
	v_add_f32_dpp v245, v245, v245 row_ror:8 row_mask:0xf bank_mask:0x3
	v_add_f32_dpp v246, v246, v246 row_ror:8 row_mask:0xf bank_mask:0x3
	v_add_f32_dpp v247, v247, v247 row_ror:8 row_mask:0xf bank_mask:0x3
	v_add_f32_dpp v240, v248, v248 row_ror:8 row_mask:0xf bank_mask:0xc
	v_add_f32_dpp v241, v249, v249 row_ror:8 row_mask:0xf bank_mask:0xc
	v_add_f32_dpp v242, v150, v150 row_ror:8 row_mask:0xf bank_mask:0xc
	v_add_f32_dpp v243, v151, v151 row_ror:8 row_mask:0xf bank_mask:0xc
	v_add_f32_dpp v244, v26, v26 row_ror:8 row_mask:0xf bank_mask:0xc
	v_add_f32_dpp v245, v27, v27 row_ror:8 row_mask:0xf bank_mask:0xc
	v_add_f32_dpp v246, v62, v62 row_ror:8 row_mask:0xf bank_mask:0xc
	v_add_f32_dpp v247, v63, v63 row_ror:8 row_mask:0xf bank_mask:0xc
	v_add_f32_dpp v240, v240, v240 row_ror:12 row_mask:0xf bank_mask:0x5
	v_add_f32_dpp v241, v241, v241 row_ror:12 row_mask:0xf bank_mask:0x5
	v_add_f32_dpp v242, v242, v242 row_ror:12 row_mask:0xf bank_mask:0x5
	v_add_f32_dpp v243, v243, v243 row_ror:12 row_mask:0xf bank_mask:0x5
	v_add_f32_dpp v240, v244, v244 row_ror:4 row_mask:0xf bank_mask:0xa
	v_add_f32_dpp v241, v245, v245 row_ror:4 row_mask:0xf bank_mask:0xa
	v_add_f32_dpp v242, v246, v246 row_ror:4 row_mask:0xf bank_mask:0xa
	v_add_f32_dpp v243, v247, v247 row_ror:4 row_mask:0xf bank_mask:0xa
	v_lshl_add_u32 v25, v34, 4, v18
	v_add_f32_dpp v240, v240, v240 quad_perm:[1,0,3,2] row_mask:0xf bank_mask:0xf
	v_add_f32_dpp v241, v241, v241 quad_perm:[1,0,3,2] row_mask:0xf bank_mask:0xf
	v_add_f32_dpp v242, v242, v242 quad_perm:[1,0,3,2] row_mask:0xf bank_mask:0xf
	v_add_f32_dpp v243, v243, v243 quad_perm:[1,0,3,2] row_mask:0xf bank_mask:0xf
	v_add_f32_dpp v240, v240, v240 quad_perm:[2,3,0,1] row_mask:0xf bank_mask:0xf
	v_add_f32_dpp v241, v241, v241 quad_perm:[2,3,0,1] row_mask:0xf bank_mask:0xf
	v_add_f32_dpp v242, v242, v242 quad_perm:[2,3,0,1] row_mask:0xf bank_mask:0xf
	v_add_f32_dpp v243, v243, v243 quad_perm:[2,3,0,1] row_mask:0xf bank_mask:0xf
	v_cmp_eq_u32_e32 vcc, 1, v19
	s_nop 1
	v_cndmask_b32_e32 v24, v240, v241, vcc
	v_cmp_eq_u32_e32 vcc, 2, v19
	s_nop 1
	v_cndmask_b32_e32 v24, v24, v242, vcc
	v_cmp_eq_u32_e32 vcc, 3, v19
	s_nop 1
	v_cndmask_b32_e32 v24, v24, v243, vcc
	ds_write_b32 v25, v24 offset:21504
	s_cmpk_eq_i32 s9, 0x7e0
	s_cbranch_scc1 .LBB0_451
	s_mov_b32 s13, s12
	s_mov_b32 s11, s9
	s_branch .LBB0_423

.LBB0_1389:
	s_or_b64 exec, exec, s[0:1]
	v_bfe_u32 v82, v86, 4, 2
	v_and_b32_e32 v83, -4, v85
	v_lshlrev_b32_e32 v93, 2, v83
	v_lshlrev_b32_e32 v94, 2, v82
	v_add3_u32 v90, 0, v93, v94
	v_add_u32_e32 v21, 0x5000, v90
	v_lshl_add_u32 v84, v36, 2, 0
	ds_read2_b32 v[26:27], v21 offset1:16
	ds_read_b128 v[16:19], v84 offset:12288
	ds_read_b128 v[22:25], v84
	ds_read_b128 v[52:55], v84 offset:256
	ds_read_b128 v[56:59], v84 offset:4096
	ds_read_b128 v[60:63], v84 offset:4352
	ds_read_b128 v[64:67], v84 offset:8192
	ds_read_b128 v[68:71], v84 offset:8448
	ds_read_b128 v[96:99], v84 offset:12544
	ds_read_b128 v[100:103], v84 offset:16384
	ds_read_b128 v[104:107], v84 offset:16640
	s_waitcnt lgkmcnt(9)
	v_pk_mul_f32 v[18:19], v[18:19], 0 op_sel_hi:[1,0]
	v_cmp_eq_u32_e64 s[6:7], 0, v81
	v_pk_fma_f32 v[16:17], v[16:17], 0, v[18:19] op_sel_hi:[1,0,1]
	v_mov_b32_e32 v20, v27
	v_add_f32_e32 v16, v16, v17
	s_nop 1
	v_add_f32_dpp v16, v16, v16 row_ror:8 row_mask:0xf bank_mask:0xf bound_ctrl:1
	s_nop 1
	v_add_f32_dpp v16, v16, v16 row_ror:4 row_mask:0xf bank_mask:0xf bound_ctrl:1
	s_nop 1
	v_add_f32_dpp v16, v16, v16 row_ror:2 row_mask:0xf bank_mask:0xf bound_ctrl:1
	s_nop 1
	v_add_f32_dpp v16, v16, v16 row_ror:1 row_mask:0xf bank_mask:0xf bound_ctrl:1
	s_waitcnt lgkmcnt(1)
	v_pk_mul_f32 v[18:19], v[100:101], v[16:17] op_sel_hi:[1,0]
	v_pk_mul_f32 v[16:17], v[102:103], v[16:17] op_sel_hi:[1,0]
	v_pk_fma_f32 v[18:19], v[26:27], v[56:57], v[18:19] op_sel_hi:[0,1,1] neg_lo:[0,0,1] neg_hi:[0,0,1]
	v_pk_fma_f32 v[16:17], v[26:27], v[58:59], v[16:17] op_sel_hi:[0,1,1] neg_lo:[0,0,1] neg_hi:[0,0,1]
	v_pk_fma_f32 v[56:57], v[66:67], 0, v[16:17] op_sel_hi:[1,0,1]
	v_pk_fma_f32 v[18:19], v[64:65], 0, v[18:19] op_sel_hi:[1,0,1]
	v_pk_mul_f32 v[16:17], v[24:25], v[56:57]
	s_nop 0
	v_pk_fma_f32 v[16:17], v[22:23], v[18:19], v[16:17]
	s_nop 0
	v_add_f32_e32 v26, v16, v17
	v_pk_mul_f32 v[16:17], v[98:99], v[56:57]
	s_nop 0
	v_pk_fma_f32 v[16:17], v[96:97], v[18:19], v[16:17]
	s_nop 0
	v_add_f32_e32 v16, v16, v17
	s_nop 1
	v_add_f32_dpp v16, v16, v16 row_ror:8 row_mask:0xf bank_mask:0xf bound_ctrl:1
	s_nop 1
	v_add_f32_dpp v16, v16, v16 row_ror:4 row_mask:0xf bank_mask:0xf bound_ctrl:1
	s_nop 1
	v_add_f32_dpp v16, v16, v16 row_ror:2 row_mask:0xf bank_mask:0xf bound_ctrl:1
	s_nop 1
	v_add_f32_dpp v16, v16, v16 row_ror:1 row_mask:0xf bank_mask:0xf bound_ctrl:1
	s_waitcnt lgkmcnt(0)
	v_pk_mul_f32 v[22:23], v[104:105], v[16:17] op_sel_hi:[1,0]
	v_pk_mul_f32 v[16:17], v[106:107], v[16:17] op_sel_hi:[1,0]
	v_pk_fma_f32 v[22:23], v[20:21], v[60:61], v[22:23] op_sel_hi:[0,1,1] neg_lo:[0,0,1] neg_hi:[0,0,1]
	v_pk_fma_f32 v[24:25], v[20:21], v[62:63], v[16:17] op_sel_hi:[0,1,1] neg_lo:[0,0,1] neg_hi:[0,0,1]
	v_pk_fma_f32 v[16:17], v[68:69], v[18:19], v[22:23]
	v_pk_fma_f32 v[18:19], v[70:71], v[56:57], v[24:25]
	v_mov_b32_e32 v25, v28
	v_pk_mul_f32 v[22:23], v[54:55], v[18:19]
	s_nop 0
	v_pk_fma_f32 v[22:23], v[52:53], v[16:17], v[22:23]
	s_nop 0
	v_add_f32_e32 v20, v22, v23
	v_add_f32_dpp v22, v26, v26 row_ror:8 row_mask:0xf bank_mask:0xf bound_ctrl:1
	v_mov_b32_e32 v23, v28
	v_add_f32_dpp v20, v20, v20 row_ror:8 row_mask:0xf bank_mask:0xf bound_ctrl:1
	v_add_f32_dpp v22, v22, v22 row_ror:4 row_mask:0xf bank_mask:0xf bound_ctrl:1
	s_nop 0
	v_add_f32_dpp v20, v20, v20 row_ror:4 row_mask:0xf bank_mask:0xf bound_ctrl:1
	v_add_f32_dpp v22, v22, v22 row_ror:2 row_mask:0xf bank_mask:0xf bound_ctrl:1
	s_nop 0
	v_add_f32_dpp v24, v20, v20 row_ror:2 row_mask:0xf bank_mask:0xf bound_ctrl:1
	v_mov_b32_dpp v23, v22 row_ror:1 row_mask:0xf bank_mask:0xf
	v_add_u32_e32 v20, 0x5400, v90
	v_mov_b32_dpp v25, v24 row_ror:1 row_mask:0xf bank_mask:0xf
	s_and_saveexec_b64 s[0:1], s[6:7]
	v_add_f32_e32 v22, v22, v23
	v_add_f32_e32 v23, v24, v25
	ds_write2_b32 v20, v22, v23 offset1:16
	s_or_b64 exec, exec, s[0:1]
	ds_read2_b32 v[26:27], v21 offset0:32 offset1:48
	ds_read_b128 v[22:25], v84 offset:12800
	ds_read_b128 v[52:55], v84 offset:512
	ds_read_b128 v[56:59], v84 offset:768
	ds_read_b128 v[60:63], v84 offset:4608
	ds_read_b128 v[64:67], v84 offset:4864
	ds_read_b128 v[68:71], v84 offset:8704
	ds_read_b128 v[96:99], v84 offset:8960
	ds_read_b128 v[100:103], v84 offset:13056
	ds_read_b128 v[104:107], v84 offset:16896
	ds_read_b128 v[108:111], v84 offset:17152
	s_waitcnt lgkmcnt(9)
	v_pk_mul_f32 v[24:25], v[18:19], v[24:25]
	s_nop 0
	v_pk_fma_f32 v[22:23], v[16:17], v[22:23], v[24:25]
	s_nop 0
	v_add_f32_e32 v22, v22, v23
	s_nop 1
	v_add_f32_dpp v22, v22, v22 row_ror:8 row_mask:0xf bank_mask:0xf bound_ctrl:1
	s_nop 1
	v_add_f32_dpp v22, v22, v22 row_ror:4 row_mask:0xf bank_mask:0xf bound_ctrl:1
	s_nop 1
	v_add_f32_dpp v22, v22, v22 row_ror:2 row_mask:0xf bank_mask:0xf bound_ctrl:1
	s_nop 1
	v_add_f32_dpp v22, v22, v22 row_ror:1 row_mask:0xf bank_mask:0xf bound_ctrl:1
	s_waitcnt lgkmcnt(1)
	v_pk_mul_f32 v[24:25], v[104:105], v[22:23] op_sel_hi:[1,0]
	v_pk_mul_f32 v[22:23], v[106:107], v[22:23] op_sel_hi:[1,0]
	v_pk_fma_f32 v[24:25], v[26:27], v[60:61], v[24:25] op_sel_hi:[0,1,1] neg_lo:[0,0,1] neg_hi:[0,0,1]
	v_pk_fma_f32 v[22:23], v[26:27], v[62:63], v[22:23] op_sel_hi:[0,1,1] neg_lo:[0,0,1] neg_hi:[0,0,1]
	v_pk_fma_f32 v[18:19], v[18:19], v[70:71], v[22:23]
	v_pk_fma_f32 v[16:17], v[16:17], v[68:69], v[24:25]
	v_pk_mul_f32 v[22:23], v[54:55], v[18:19]
	v_mov_b32_e32 v24, v27
	v_pk_fma_f32 v[22:23], v[52:53], v[16:17], v[22:23]
	s_nop 0
	v_add_f32_e32 v25, v22, v23
	v_pk_mul_f32 v[22:23], v[102:103], v[18:19]
	s_nop 0
	v_pk_fma_f32 v[22:23], v[100:101], v[16:17], v[22:23]
	s_nop 0
	v_add_f32_e32 v22, v22, v23
	s_nop 1
	v_add_f32_dpp v22, v22, v22 row_ror:8 row_mask:0xf bank_mask:0xf bound_ctrl:1
	s_nop 1
	v_add_f32_dpp v22, v22, v22 row_ror:4 row_mask:0xf bank_mask:0xf bound_ctrl:1
	s_nop 1
	v_add_f32_dpp v22, v22, v22 row_ror:2 row_mask:0xf bank_mask:0xf bound_ctrl:1
	s_nop 1
	v_add_f32_dpp v22, v22, v22 row_ror:1 row_mask:0xf bank_mask:0xf bound_ctrl:1
	s_waitcnt lgkmcnt(0)
	v_pk_mul_f32 v[26:27], v[108:109], v[22:23] op_sel_hi:[1,0]
	v_pk_mul_f32 v[22:23], v[110:111], v[22:23] op_sel_hi:[1,0]
	v_pk_fma_f32 v[26:27], v[24:25], v[64:65], v[26:27] op_sel_hi:[0,1,1] neg_lo:[0,0,1] neg_hi:[0,0,1]
	v_pk_fma_f32 v[22:23], v[24:25], v[66:67], v[22:23] op_sel_hi:[0,1,1] neg_lo:[0,0,1] neg_hi:[0,0,1]
	v_pk_fma_f32 v[18:19], v[98:99], v[18:19], v[22:23]
	v_pk_fma_f32 v[16:17], v[96:97], v[16:17], v[26:27]
	v_pk_mul_f32 v[22:23], v[58:59], v[18:19]
	s_nop 0
	v_pk_fma_f32 v[22:23], v[56:57], v[16:17], v[22:23]
	s_nop 0
	v_add_f32_e32 v24, v22, v23
	v_add_f32_dpp v22, v25, v25 row_ror:8 row_mask:0xf bank_mask:0xf bound_ctrl:1
	v_mov_b32_e32 v23, v28
	v_add_f32_dpp v24, v24, v24 row_ror:8 row_mask:0xf bank_mask:0xf bound_ctrl:1
	v_add_f32_dpp v22, v22, v22 row_ror:4 row_mask:0xf bank_mask:0xf bound_ctrl:1
	v_mov_b32_e32 v25, v28
	v_add_f32_dpp v24, v24, v24 row_ror:4 row_mask:0xf bank_mask:0xf bound_ctrl:1
	v_add_f32_dpp v22, v22, v22 row_ror:2 row_mask:0xf bank_mask:0xf bound_ctrl:1
	s_nop 0
	v_add_f32_dpp v24, v24, v24 row_ror:2 row_mask:0xf bank_mask:0xf bound_ctrl:1
	v_mov_b32_dpp v23, v22 row_ror:1 row_mask:0xf bank_mask:0xf
	s_nop 0
	v_mov_b32_dpp v25, v24 row_ror:1 row_mask:0xf bank_mask:0xf
	s_and_saveexec_b64 s[0:1], s[6:7]
	v_add_f32_e32 v22, v22, v23
	v_add_f32_e32 v23, v24, v25
	ds_write2_b32 v20, v22, v23 offset0:32 offset1:48
	s_or_b64 exec, exec, s[0:1]
	ds_read2_b32 v[26:27], v21 offset0:64 offset1:80
	ds_read_b128 v[22:25], v84 offset:13312
	ds_read_b128 v[52:55], v84 offset:1024
	ds_read_b128 v[56:59], v84 offset:1280
	ds_read_b128 v[60:63], v84 offset:5120
	ds_read_b128 v[64:67], v84 offset:5376
	ds_read_b128 v[68:71], v84 offset:9216
	ds_read_b128 v[96:99], v84 offset:9472
	ds_read_b128 v[100:103], v84 offset:13568
	ds_read_b128 v[104:107], v84 offset:17408
	ds_read_b128 v[108:111], v84 offset:17664
	s_waitcnt lgkmcnt(9)
	v_pk_mul_f32 v[24:25], v[18:19], v[24:25]
	s_nop 0
	v_pk_fma_f32 v[22:23], v[16:17], v[22:23], v[24:25]
	s_nop 0
	v_add_f32_e32 v22, v22, v23
	s_nop 1
	v_add_f32_dpp v22, v22, v22 row_ror:8 row_mask:0xf bank_mask:0xf bound_ctrl:1
	s_nop 1
	v_add_f32_dpp v22, v22, v22 row_ror:4 row_mask:0xf bank_mask:0xf bound_ctrl:1
	s_nop 1
	v_add_f32_dpp v22, v22, v22 row_ror:2 row_mask:0xf bank_mask:0xf bound_ctrl:1
	s_nop 1
	v_add_f32_dpp v22, v22, v22 row_ror:1 row_mask:0xf bank_mask:0xf bound_ctrl:1
	s_waitcnt lgkmcnt(1)
	v_pk_mul_f32 v[24:25], v[104:105], v[22:23] op_sel_hi:[1,0]
	v_pk_mul_f32 v[22:23], v[106:107], v[22:23] op_sel_hi:[1,0]
	v_pk_fma_f32 v[24:25], v[26:27], v[60:61], v[24:25] op_sel_hi:[0,1,1] neg_lo:[0,0,1] neg_hi:[0,0,1]
	v_pk_fma_f32 v[22:23], v[26:27], v[62:63], v[22:23] op_sel_hi:[0,1,1] neg_lo:[0,0,1] neg_hi:[0,0,1]
	v_pk_fma_f32 v[18:19], v[18:19], v[70:71], v[22:23]
	v_pk_fma_f32 v[16:17], v[16:17], v[68:69], v[24:25]
	v_pk_mul_f32 v[22:23], v[54:55], v[18:19]
	v_mov_b32_e32 v24, v27
	v_pk_fma_f32 v[22:23], v[52:53], v[16:17], v[22:23]
	s_nop 0
	v_add_f32_e32 v25, v22, v23
	v_pk_mul_f32 v[22:23], v[102:103], v[18:19]
	s_nop 0
	v_pk_fma_f32 v[22:23], v[100:101], v[16:17], v[22:23]
	s_nop 0
	v_add_f32_e32 v22, v22, v23
	s_nop 1
	v_add_f32_dpp v22, v22, v22 row_ror:8 row_mask:0xf bank_mask:0xf bound_ctrl:1
	s_nop 1
	v_add_f32_dpp v22, v22, v22 row_ror:4 row_mask:0xf bank_mask:0xf bound_ctrl:1
	s_nop 1
	v_add_f32_dpp v22, v22, v22 row_ror:2 row_mask:0xf bank_mask:0xf bound_ctrl:1
	s_nop 1
	v_add_f32_dpp v22, v22, v22 row_ror:1 row_mask:0xf bank_mask:0xf bound_ctrl:1
	s_waitcnt lgkmcnt(0)
	v_pk_mul_f32 v[26:27], v[108:109], v[22:23] op_sel_hi:[1,0]
	v_pk_mul_f32 v[22:23], v[110:111], v[22:23] op_sel_hi:[1,0]
	v_pk_fma_f32 v[26:27], v[24:25], v[64:65], v[26:27] op_sel_hi:[0,1,1] neg_lo:[0,0,1] neg_hi:[0,0,1]
	v_pk_fma_f32 v[22:23], v[24:25], v[66:67], v[22:23] op_sel_hi:[0,1,1] neg_lo:[0,0,1] neg_hi:[0,0,1]
	v_pk_fma_f32 v[18:19], v[98:99], v[18:19], v[22:23]
	v_pk_fma_f32 v[16:17], v[96:97], v[16:17], v[26:27]
	v_pk_mul_f32 v[22:23], v[58:59], v[18:19]
	s_nop 0
	v_pk_fma_f32 v[22:23], v[56:57], v[16:17], v[22:23]
	s_nop 0
	v_add_f32_e32 v24, v22, v23
	v_add_f32_dpp v22, v25, v25 row_ror:8 row_mask:0xf bank_mask:0xf bound_ctrl:1
	v_mov_b32_e32 v23, v28
	v_add_f32_dpp v24, v24, v24 row_ror:8 row_mask:0xf bank_mask:0xf bound_ctrl:1
	v_add_f32_dpp v22, v22, v22 row_ror:4 row_mask:0xf bank_mask:0xf bound_ctrl:1
	v_mov_b32_e32 v25, v28
	v_add_f32_dpp v24, v24, v24 row_ror:4 row_mask:0xf bank_mask:0xf bound_ctrl:1
	v_add_f32_dpp v22, v22, v22 row_ror:2 row_mask:0xf bank_mask:0xf bound_ctrl:1
	s_nop 0
	v_add_f32_dpp v24, v24, v24 row_ror:2 row_mask:0xf bank_mask:0xf bound_ctrl:1
	v_mov_b32_dpp v23, v22 row_ror:1 row_mask:0xf bank_mask:0xf
	s_nop 0
	v_mov_b32_dpp v25, v24 row_ror:1 row_mask:0xf bank_mask:0xf
	s_and_saveexec_b64 s[0:1], s[6:7]
	v_add_f32_e32 v22, v22, v23
	v_add_f32_e32 v23, v24, v25
	ds_write2_b32 v20, v22, v23 offset0:64 offset1:80
	s_or_b64 exec, exec, s[0:1]
	ds_read2_b32 v[26:27], v21 offset0:96 offset1:112
	ds_read_b128 v[22:25], v84 offset:13824
	ds_read_b128 v[52:55], v84 offset:1536
	ds_read_b128 v[56:59], v84 offset:1792
	ds_read_b128 v[60:63], v84 offset:5632
	ds_read_b128 v[64:67], v84 offset:5888
	ds_read_b128 v[68:71], v84 offset:9728
	ds_read_b128 v[96:99], v84 offset:9984
	ds_read_b128 v[100:103], v84 offset:14080
	ds_read_b128 v[104:107], v84 offset:17920
	ds_read_b128 v[108:111], v84 offset:18176
	s_waitcnt lgkmcnt(9)
	v_pk_mul_f32 v[24:25], v[18:19], v[24:25]
	s_nop 0
	v_pk_fma_f32 v[22:23], v[16:17], v[22:23], v[24:25]
	s_nop 0
	v_add_f32_e32 v22, v22, v23
	s_nop 1
	v_add_f32_dpp v22, v22, v22 row_ror:8 row_mask:0xf bank_mask:0xf bound_ctrl:1
	s_nop 1
	v_add_f32_dpp v22, v22, v22 row_ror:4 row_mask:0xf bank_mask:0xf bound_ctrl:1
	s_nop 1
	v_add_f32_dpp v22, v22, v22 row_ror:2 row_mask:0xf bank_mask:0xf bound_ctrl:1
	s_nop 1
	v_add_f32_dpp v22, v22, v22 row_ror:1 row_mask:0xf bank_mask:0xf bound_ctrl:1
	s_waitcnt lgkmcnt(1)
	v_pk_mul_f32 v[24:25], v[104:105], v[22:23] op_sel_hi:[1,0]
	v_pk_mul_f32 v[22:23], v[106:107], v[22:23] op_sel_hi:[1,0]
	v_pk_fma_f32 v[24:25], v[26:27], v[60:61], v[24:25] op_sel_hi:[0,1,1] neg_lo:[0,0,1] neg_hi:[0,0,1]
	v_pk_fma_f32 v[22:23], v[26:27], v[62:63], v[22:23] op_sel_hi:[0,1,1] neg_lo:[0,0,1] neg_hi:[0,0,1]
	v_pk_fma_f32 v[18:19], v[18:19], v[70:71], v[22:23]
	v_pk_fma_f32 v[16:17], v[16:17], v[68:69], v[24:25]
	v_pk_mul_f32 v[22:23], v[54:55], v[18:19]
	v_mov_b32_e32 v24, v27
	v_pk_fma_f32 v[22:23], v[52:53], v[16:17], v[22:23]
	s_nop 0
	v_add_f32_e32 v25, v22, v23
	v_pk_mul_f32 v[22:23], v[102:103], v[18:19]
	s_nop 0
	v_pk_fma_f32 v[22:23], v[100:101], v[16:17], v[22:23]
	s_nop 0
	v_add_f32_e32 v22, v22, v23
	s_nop 1
	v_add_f32_dpp v22, v22, v22 row_ror:8 row_mask:0xf bank_mask:0xf bound_ctrl:1
	s_nop 1
	v_add_f32_dpp v22, v22, v22 row_ror:4 row_mask:0xf bank_mask:0xf bound_ctrl:1
	s_nop 1
	v_add_f32_dpp v22, v22, v22 row_ror:2 row_mask:0xf bank_mask:0xf bound_ctrl:1
	s_nop 1
	v_add_f32_dpp v22, v22, v22 row_ror:1 row_mask:0xf bank_mask:0xf bound_ctrl:1
	s_waitcnt lgkmcnt(0)
	v_pk_mul_f32 v[26:27], v[108:109], v[22:23] op_sel_hi:[1,0]
	v_pk_mul_f32 v[22:23], v[110:111], v[22:23] op_sel_hi:[1,0]
	v_pk_fma_f32 v[26:27], v[24:25], v[64:65], v[26:27] op_sel_hi:[0,1,1] neg_lo:[0,0,1] neg_hi:[0,0,1]
	v_pk_fma_f32 v[22:23], v[24:25], v[66:67], v[22:23] op_sel_hi:[0,1,1] neg_lo:[0,0,1] neg_hi:[0,0,1]
	v_pk_fma_f32 v[18:19], v[98:99], v[18:19], v[22:23]
	v_pk_fma_f32 v[16:17], v[96:97], v[16:17], v[26:27]
	v_pk_mul_f32 v[22:23], v[58:59], v[18:19]
	s_nop 0
	v_pk_fma_f32 v[22:23], v[56:57], v[16:17], v[22:23]
	s_nop 0
	v_add_f32_e32 v24, v22, v23
	v_add_f32_dpp v22, v25, v25 row_ror:8 row_mask:0xf bank_mask:0xf bound_ctrl:1
	v_mov_b32_e32 v23, v28
	v_add_f32_dpp v24, v24, v24 row_ror:8 row_mask:0xf bank_mask:0xf bound_ctrl:1
	v_add_f32_dpp v22, v22, v22 row_ror:4 row_mask:0xf bank_mask:0xf bound_ctrl:1
	v_mov_b32_e32 v25, v28
	v_add_f32_dpp v24, v24, v24 row_ror:4 row_mask:0xf bank_mask:0xf bound_ctrl:1
	v_add_f32_dpp v22, v22, v22 row_ror:2 row_mask:0xf bank_mask:0xf bound_ctrl:1
	s_nop 0
	v_add_f32_dpp v24, v24, v24 row_ror:2 row_mask:0xf bank_mask:0xf bound_ctrl:1
	v_mov_b32_dpp v23, v22 row_ror:1 row_mask:0xf bank_mask:0xf
	s_nop 0
	v_mov_b32_dpp v25, v24 row_ror:1 row_mask:0xf bank_mask:0xf
	s_and_saveexec_b64 s[0:1], s[6:7]
	v_add_f32_e32 v22, v22, v23
	v_add_f32_e32 v23, v24, v25
	ds_write2_b32 v20, v22, v23 offset0:96 offset1:112
	s_or_b64 exec, exec, s[0:1]
	ds_read2_b32 v[26:27], v21 offset0:128 offset1:144
	ds_read_b128 v[22:25], v84 offset:14336
	ds_read_b128 v[52:55], v84 offset:2048
	ds_read_b128 v[56:59], v84 offset:2304
	ds_read_b128 v[60:63], v84 offset:6144
	ds_read_b128 v[64:67], v84 offset:6400
	ds_read_b128 v[68:71], v84 offset:10240
	ds_read_b128 v[96:99], v84 offset:10496
	ds_read_b128 v[100:103], v84 offset:14592
	ds_read_b128 v[104:107], v84 offset:18432
	ds_read_b128 v[108:111], v84 offset:18688
	s_waitcnt lgkmcnt(9)
	v_pk_mul_f32 v[24:25], v[18:19], v[24:25]
	s_nop 0
	v_pk_fma_f32 v[22:23], v[16:17], v[22:23], v[24:25]
	s_nop 0
	v_add_f32_e32 v22, v22, v23
	s_nop 1
	v_add_f32_dpp v22, v22, v22 row_ror:8 row_mask:0xf bank_mask:0xf bound_ctrl:1
	s_nop 1
	v_add_f32_dpp v22, v22, v22 row_ror:4 row_mask:0xf bank_mask:0xf bound_ctrl:1
	s_nop 1
	v_add_f32_dpp v22, v22, v22 row_ror:2 row_mask:0xf bank_mask:0xf bound_ctrl:1
	s_nop 1
	v_add_f32_dpp v22, v22, v22 row_ror:1 row_mask:0xf bank_mask:0xf bound_ctrl:1
	s_waitcnt lgkmcnt(1)
	v_pk_mul_f32 v[24:25], v[104:105], v[22:23] op_sel_hi:[1,0]
	v_pk_mul_f32 v[22:23], v[106:107], v[22:23] op_sel_hi:[1,0]
	v_pk_fma_f32 v[24:25], v[26:27], v[60:61], v[24:25] op_sel_hi:[0,1,1] neg_lo:[0,0,1] neg_hi:[0,0,1]
	v_pk_fma_f32 v[22:23], v[26:27], v[62:63], v[22:23] op_sel_hi:[0,1,1] neg_lo:[0,0,1] neg_hi:[0,0,1]
	v_pk_fma_f32 v[18:19], v[18:19], v[70:71], v[22:23]
	v_pk_fma_f32 v[16:17], v[16:17], v[68:69], v[24:25]
	v_pk_mul_f32 v[22:23], v[54:55], v[18:19]
	v_mov_b32_e32 v24, v27
	v_pk_fma_f32 v[22:23], v[52:53], v[16:17], v[22:23]
	s_nop 0
	v_add_f32_e32 v25, v22, v23
	v_pk_mul_f32 v[22:23], v[102:103], v[18:19]
	s_nop 0
	v_pk_fma_f32 v[22:23], v[100:101], v[16:17], v[22:23]
	s_nop 0
	v_add_f32_e32 v22, v22, v23
	s_nop 1
	v_add_f32_dpp v22, v22, v22 row_ror:8 row_mask:0xf bank_mask:0xf bound_ctrl:1
	s_nop 1
	v_add_f32_dpp v22, v22, v22 row_ror:4 row_mask:0xf bank_mask:0xf bound_ctrl:1
	s_nop 1
	v_add_f32_dpp v22, v22, v22 row_ror:2 row_mask:0xf bank_mask:0xf bound_ctrl:1
	s_nop 1
	v_add_f32_dpp v22, v22, v22 row_ror:1 row_mask:0xf bank_mask:0xf bound_ctrl:1
	s_waitcnt lgkmcnt(0)
	v_pk_mul_f32 v[26:27], v[108:109], v[22:23] op_sel_hi:[1,0]
	v_pk_mul_f32 v[22:23], v[110:111], v[22:23] op_sel_hi:[1,0]
	v_pk_fma_f32 v[26:27], v[24:25], v[64:65], v[26:27] op_sel_hi:[0,1,1] neg_lo:[0,0,1] neg_hi:[0,0,1]
	v_pk_fma_f32 v[22:23], v[24:25], v[66:67], v[22:23] op_sel_hi:[0,1,1] neg_lo:[0,0,1] neg_hi:[0,0,1]
	v_pk_fma_f32 v[18:19], v[98:99], v[18:19], v[22:23]
	v_pk_fma_f32 v[16:17], v[96:97], v[16:17], v[26:27]
	v_pk_mul_f32 v[22:23], v[58:59], v[18:19]
	s_nop 0
	v_pk_fma_f32 v[22:23], v[56:57], v[16:17], v[22:23]
	s_nop 0
	v_add_f32_e32 v24, v22, v23
	v_add_f32_dpp v22, v25, v25 row_ror:8 row_mask:0xf bank_mask:0xf bound_ctrl:1
	v_mov_b32_e32 v23, v28
	v_add_f32_dpp v24, v24, v24 row_ror:8 row_mask:0xf bank_mask:0xf bound_ctrl:1
	v_add_f32_dpp v22, v22, v22 row_ror:4 row_mask:0xf bank_mask:0xf bound_ctrl:1
	v_mov_b32_e32 v25, v28
	v_add_f32_dpp v24, v24, v24 row_ror:4 row_mask:0xf bank_mask:0xf bound_ctrl:1
	v_add_f32_dpp v22, v22, v22 row_ror:2 row_mask:0xf bank_mask:0xf bound_ctrl:1
	s_nop 0
	v_add_f32_dpp v24, v24, v24 row_ror:2 row_mask:0xf bank_mask:0xf bound_ctrl:1
	v_mov_b32_dpp v23, v22 row_ror:1 row_mask:0xf bank_mask:0xf
	s_nop 0
	v_mov_b32_dpp v25, v24 row_ror:1 row_mask:0xf bank_mask:0xf
	s_and_saveexec_b64 s[0:1], s[6:7]
	v_add_f32_e32 v22, v22, v23
	v_add_f32_e32 v23, v24, v25
	ds_write2_b32 v20, v22, v23 offset0:128 offset1:144
	s_or_b64 exec, exec, s[0:1]
	ds_read2_b32 v[26:27], v21 offset0:160 offset1:176
	ds_read_b128 v[22:25], v84 offset:14848
	ds_read_b128 v[52:55], v84 offset:2560
	ds_read_b128 v[56:59], v84 offset:2816
	ds_read_b128 v[60:63], v84 offset:6656
	ds_read_b128 v[64:67], v84 offset:6912
	ds_read_b128 v[68:71], v84 offset:10752
	ds_read_b128 v[96:99], v84 offset:11008
	ds_read_b128 v[100:103], v84 offset:15104
	ds_read_b128 v[104:107], v84 offset:18944
	ds_read_b128 v[108:111], v84 offset:19200
	s_waitcnt lgkmcnt(9)
	v_pk_mul_f32 v[24:25], v[18:19], v[24:25]
	s_nop 0
	v_pk_fma_f32 v[22:23], v[16:17], v[22:23], v[24:25]
	s_nop 0
	v_add_f32_e32 v22, v22, v23
	s_nop 1
	v_add_f32_dpp v22, v22, v22 row_ror:8 row_mask:0xf bank_mask:0xf bound_ctrl:1
	s_nop 1
	v_add_f32_dpp v22, v22, v22 row_ror:4 row_mask:0xf bank_mask:0xf bound_ctrl:1
	s_nop 1
	v_add_f32_dpp v22, v22, v22 row_ror:2 row_mask:0xf bank_mask:0xf bound_ctrl:1
	s_nop 1
	v_add_f32_dpp v22, v22, v22 row_ror:1 row_mask:0xf bank_mask:0xf bound_ctrl:1
	s_waitcnt lgkmcnt(1)
	v_pk_mul_f32 v[24:25], v[104:105], v[22:23] op_sel_hi:[1,0]
	v_pk_mul_f32 v[22:23], v[106:107], v[22:23] op_sel_hi:[1,0]
	v_pk_fma_f32 v[24:25], v[26:27], v[60:61], v[24:25] op_sel_hi:[0,1,1] neg_lo:[0,0,1] neg_hi:[0,0,1]
	v_pk_fma_f32 v[22:23], v[26:27], v[62:63], v[22:23] op_sel_hi:[0,1,1] neg_lo:[0,0,1] neg_hi:[0,0,1]
	v_pk_fma_f32 v[18:19], v[18:19], v[70:71], v[22:23]
	v_pk_fma_f32 v[16:17], v[16:17], v[68:69], v[24:25]
	v_pk_mul_f32 v[22:23], v[54:55], v[18:19]
	v_mov_b32_e32 v24, v27
	v_pk_fma_f32 v[22:23], v[52:53], v[16:17], v[22:23]
	s_nop 0
	v_add_f32_e32 v25, v22, v23
	v_pk_mul_f32 v[22:23], v[102:103], v[18:19]
	s_nop 0
	v_pk_fma_f32 v[22:23], v[100:101], v[16:17], v[22:23]
	s_nop 0
	v_add_f32_e32 v22, v22, v23
	s_nop 1
	v_add_f32_dpp v22, v22, v22 row_ror:8 row_mask:0xf bank_mask:0xf bound_ctrl:1
	s_nop 1
	v_add_f32_dpp v22, v22, v22 row_ror:4 row_mask:0xf bank_mask:0xf bound_ctrl:1
	s_nop 1
	v_add_f32_dpp v22, v22, v22 row_ror:2 row_mask:0xf bank_mask:0xf bound_ctrl:1
	s_nop 1
	v_add_f32_dpp v22, v22, v22 row_ror:1 row_mask:0xf bank_mask:0xf bound_ctrl:1
	s_waitcnt lgkmcnt(0)
	v_pk_mul_f32 v[26:27], v[108:109], v[22:23] op_sel_hi:[1,0]
	v_pk_mul_f32 v[22:23], v[110:111], v[22:23] op_sel_hi:[1,0]
	v_pk_fma_f32 v[26:27], v[24:25], v[64:65], v[26:27] op_sel_hi:[0,1,1] neg_lo:[0,0,1] neg_hi:[0,0,1]
	v_pk_fma_f32 v[22:23], v[24:25], v[66:67], v[22:23] op_sel_hi:[0,1,1] neg_lo:[0,0,1] neg_hi:[0,0,1]
	v_pk_fma_f32 v[18:19], v[98:99], v[18:19], v[22:23]
	v_pk_fma_f32 v[16:17], v[96:97], v[16:17], v[26:27]
	v_pk_mul_f32 v[22:23], v[58:59], v[18:19]
	s_nop 0
	v_pk_fma_f32 v[22:23], v[56:57], v[16:17], v[22:23]
	s_nop 0
	v_add_f32_e32 v24, v22, v23
	v_add_f32_dpp v22, v25, v25 row_ror:8 row_mask:0xf bank_mask:0xf bound_ctrl:1
	v_mov_b32_e32 v23, v28
	v_add_f32_dpp v24, v24, v24 row_ror:8 row_mask:0xf bank_mask:0xf bound_ctrl:1
	v_add_f32_dpp v22, v22, v22 row_ror:4 row_mask:0xf bank_mask:0xf bound_ctrl:1
	v_mov_b32_e32 v25, v28
	v_add_f32_dpp v24, v24, v24 row_ror:4 row_mask:0xf bank_mask:0xf bound_ctrl:1
	v_add_f32_dpp v22, v22, v22 row_ror:2 row_mask:0xf bank_mask:0xf bound_ctrl:1
	s_nop 0
	v_add_f32_dpp v24, v24, v24 row_ror:2 row_mask:0xf bank_mask:0xf bound_ctrl:1
	v_mov_b32_dpp v23, v22 row_ror:1 row_mask:0xf bank_mask:0xf
	s_nop 0
	v_mov_b32_dpp v25, v24 row_ror:1 row_mask:0xf bank_mask:0xf
	s_and_saveexec_b64 s[0:1], s[6:7]
	v_add_f32_e32 v22, v22, v23
	v_add_f32_e32 v23, v24, v25
	ds_write2_b32 v20, v22, v23 offset0:160 offset1:176
	s_or_b64 exec, exec, s[0:1]
	ds_read2_b32 v[26:27], v21 offset0:192 offset1:208
	ds_read_b128 v[22:25], v84 offset:15360
	ds_read_b128 v[52:55], v84 offset:3072
	ds_read_b128 v[56:59], v84 offset:3328
	ds_read_b128 v[60:63], v84 offset:7168
	ds_read_b128 v[64:67], v84 offset:7424
	ds_read_b128 v[68:71], v84 offset:11264
	ds_read_b128 v[96:99], v84 offset:11520
	ds_read_b128 v[100:103], v84 offset:15616
	ds_read_b128 v[104:107], v84 offset:19456
	ds_read_b128 v[108:111], v84 offset:19712
	s_waitcnt lgkmcnt(9)
	v_pk_mul_f32 v[24:25], v[18:19], v[24:25]
	s_nop 0
	v_pk_fma_f32 v[22:23], v[16:17], v[22:23], v[24:25]
	s_nop 0
	v_add_f32_e32 v22, v22, v23
	s_nop 1
	v_add_f32_dpp v22, v22, v22 row_ror:8 row_mask:0xf bank_mask:0xf bound_ctrl:1
	s_nop 1
	v_add_f32_dpp v22, v22, v22 row_ror:4 row_mask:0xf bank_mask:0xf bound_ctrl:1
	s_nop 1
	v_add_f32_dpp v22, v22, v22 row_ror:2 row_mask:0xf bank_mask:0xf bound_ctrl:1
	s_nop 1
	v_add_f32_dpp v22, v22, v22 row_ror:1 row_mask:0xf bank_mask:0xf bound_ctrl:1
	s_waitcnt lgkmcnt(1)
	v_pk_mul_f32 v[24:25], v[104:105], v[22:23] op_sel_hi:[1,0]
	v_pk_mul_f32 v[22:23], v[106:107], v[22:23] op_sel_hi:[1,0]
	v_pk_fma_f32 v[24:25], v[26:27], v[60:61], v[24:25] op_sel_hi:[0,1,1] neg_lo:[0,0,1] neg_hi:[0,0,1]
	v_pk_fma_f32 v[22:23], v[26:27], v[62:63], v[22:23] op_sel_hi:[0,1,1] neg_lo:[0,0,1] neg_hi:[0,0,1]
	v_pk_fma_f32 v[18:19], v[18:19], v[70:71], v[22:23]
	v_pk_fma_f32 v[16:17], v[16:17], v[68:69], v[24:25]
	v_pk_mul_f32 v[22:23], v[54:55], v[18:19]
	v_mov_b32_e32 v24, v27
	v_pk_fma_f32 v[22:23], v[52:53], v[16:17], v[22:23]
	s_nop 0
	v_add_f32_e32 v25, v22, v23
	v_pk_mul_f32 v[22:23], v[102:103], v[18:19]
	s_nop 0
	v_pk_fma_f32 v[22:23], v[100:101], v[16:17], v[22:23]
	s_nop 0
	v_add_f32_e32 v22, v22, v23
	s_nop 1
	v_add_f32_dpp v22, v22, v22 row_ror:8 row_mask:0xf bank_mask:0xf bound_ctrl:1
	s_nop 1
	v_add_f32_dpp v22, v22, v22 row_ror:4 row_mask:0xf bank_mask:0xf bound_ctrl:1
	s_nop 1
	v_add_f32_dpp v22, v22, v22 row_ror:2 row_mask:0xf bank_mask:0xf bound_ctrl:1
	s_nop 1
	v_add_f32_dpp v22, v22, v22 row_ror:1 row_mask:0xf bank_mask:0xf bound_ctrl:1
	s_waitcnt lgkmcnt(0)
	v_pk_mul_f32 v[26:27], v[108:109], v[22:23] op_sel_hi:[1,0]
	v_pk_mul_f32 v[22:23], v[110:111], v[22:23] op_sel_hi:[1,0]
	v_pk_fma_f32 v[26:27], v[24:25], v[64:65], v[26:27] op_sel_hi:[0,1,1] neg_lo:[0,0,1] neg_hi:[0,0,1]
	v_pk_fma_f32 v[22:23], v[24:25], v[66:67], v[22:23] op_sel_hi:[0,1,1] neg_lo:[0,0,1] neg_hi:[0,0,1]
	v_pk_fma_f32 v[18:19], v[98:99], v[18:19], v[22:23]
	v_pk_fma_f32 v[16:17], v[96:97], v[16:17], v[26:27]
	v_pk_mul_f32 v[22:23], v[58:59], v[18:19]
	s_nop 0
	v_pk_fma_f32 v[22:23], v[56:57], v[16:17], v[22:23]
	s_nop 0
	v_add_f32_e32 v24, v22, v23
	v_add_f32_dpp v22, v25, v25 row_ror:8 row_mask:0xf bank_mask:0xf bound_ctrl:1
	v_mov_b32_e32 v23, v28
	v_add_f32_dpp v24, v24, v24 row_ror:8 row_mask:0xf bank_mask:0xf bound_ctrl:1
	v_add_f32_dpp v22, v22, v22 row_ror:4 row_mask:0xf bank_mask:0xf bound_ctrl:1
	v_mov_b32_e32 v25, v28
	v_add_f32_dpp v24, v24, v24 row_ror:4 row_mask:0xf bank_mask:0xf bound_ctrl:1
	v_add_f32_dpp v22, v22, v22 row_ror:2 row_mask:0xf bank_mask:0xf bound_ctrl:1
	s_nop 0
	v_add_f32_dpp v24, v24, v24 row_ror:2 row_mask:0xf bank_mask:0xf bound_ctrl:1
	v_mov_b32_dpp v23, v22 row_ror:1 row_mask:0xf bank_mask:0xf
	s_nop 0
	v_mov_b32_dpp v25, v24 row_ror:1 row_mask:0xf bank_mask:0xf
	s_and_saveexec_b64 s[0:1], s[6:7]
	v_add_f32_e32 v22, v22, v23
	v_add_f32_e32 v23, v24, v25
	ds_write2_b32 v20, v22, v23 offset0:192 offset1:208
	s_or_b64 exec, exec, s[0:1]
	ds_read2_b32 v[26:27], v21 offset0:224 offset1:240
	ds_read_b128 v[22:25], v84 offset:15872
	ds_read_b128 v[52:55], v84 offset:3584
	ds_read_b128 v[62:65], v84 offset:3840
	ds_read_b128 v[56:59], v84 offset:7680
	ds_read_b128 v[66:69], v84 offset:7936
	ds_read_b128 v[96:99], v84 offset:11776
	ds_read_b128 v[100:103], v84 offset:12032
	ds_read_b128 v[104:107], v84 offset:16128
	ds_read_b128 v[108:111], v84 offset:19968
	ds_read_b128 v[112:115], v84 offset:20224
	s_waitcnt lgkmcnt(9)
	v_pk_mul_f32 v[24:25], v[18:19], v[24:25]
	s_nop 0
	v_pk_fma_f32 v[22:23], v[16:17], v[22:23], v[24:25]
	s_nop 0
	v_add_f32_e32 v21, v22, v23
	s_nop 1
	v_add_f32_dpp v21, v21, v21 row_ror:8 row_mask:0xf bank_mask:0xf bound_ctrl:1
	s_nop 1
	v_add_f32_dpp v21, v21, v21 row_ror:4 row_mask:0xf bank_mask:0xf bound_ctrl:1
	s_nop 1
	v_add_f32_dpp v21, v21, v21 row_ror:2 row_mask:0xf bank_mask:0xf bound_ctrl:1
	s_nop 1
	v_add_f32_dpp v22, v21, v21 row_ror:1 row_mask:0xf bank_mask:0xf bound_ctrl:1
	s_waitcnt lgkmcnt(1)
	v_pk_mul_f32 v[24:25], v[108:109], v[22:23] op_sel_hi:[1,0]
	v_pk_mul_f32 v[22:23], v[110:111], v[22:23] op_sel_hi:[1,0]
	v_pk_fma_f32 v[24:25], v[26:27], v[56:57], v[24:25] op_sel_hi:[0,1,1] neg_lo:[0,0,1] neg_hi:[0,0,1]
	v_pk_fma_f32 v[22:23], v[26:27], v[58:59], v[22:23] op_sel_hi:[0,1,1] neg_lo:[0,0,1] neg_hi:[0,0,1]
	v_pk_fma_f32 v[18:19], v[18:19], v[98:99], v[22:23]
	v_pk_fma_f32 v[16:17], v[16:17], v[96:97], v[24:25]
	v_pk_mul_f32 v[22:23], v[54:55], v[18:19]
	v_mov_b32_e32 v24, v27
	v_pk_fma_f32 v[22:23], v[52:53], v[16:17], v[22:23]
	s_nop 0
	v_add_f32_e32 v21, v22, v23
	v_pk_mul_f32 v[22:23], v[106:107], v[18:19]
	s_nop 0
	v_pk_fma_f32 v[22:23], v[104:105], v[16:17], v[22:23]
	s_nop 0
	v_add_f32_e32 v22, v22, v23
	s_nop 1
	v_add_f32_dpp v22, v22, v22 row_ror:8 row_mask:0xf bank_mask:0xf bound_ctrl:1
	s_nop 1
	v_add_f32_dpp v22, v22, v22 row_ror:4 row_mask:0xf bank_mask:0xf bound_ctrl:1
	s_nop 1
	v_add_f32_dpp v22, v22, v22 row_ror:2 row_mask:0xf bank_mask:0xf bound_ctrl:1
	s_nop 1
	v_add_f32_dpp v22, v22, v22 row_ror:1 row_mask:0xf bank_mask:0xf bound_ctrl:1
	s_waitcnt lgkmcnt(0)
	v_pk_mul_f32 v[26:27], v[112:113], v[22:23] op_sel_hi:[1,0]
	v_pk_mul_f32 v[22:23], v[114:115], v[22:23] op_sel_hi:[1,0]
	v_pk_fma_f32 v[26:27], v[24:25], v[66:67], v[26:27] op_sel_hi:[0,1,1] neg_lo:[0,0,1] neg_hi:[0,0,1]
	v_pk_fma_f32 v[22:23], v[24:25], v[68:69], v[22:23] op_sel_hi:[0,1,1] neg_lo:[0,0,1] neg_hi:[0,0,1]
	v_pk_fma_f32 v[60:61], v[102:103], v[18:19], v[22:23]
	v_pk_fma_f32 v[58:59], v[100:101], v[16:17], v[26:27]
	v_pk_mul_f32 v[16:17], v[64:65], v[60:61]
	v_mov_b32_e32 v19, v28
	v_pk_fma_f32 v[16:17], v[62:63], v[58:59], v[16:17]
	s_nop 0
	v_add_f32_e32 v18, v16, v17
	v_add_f32_dpp v16, v21, v21 row_ror:8 row_mask:0xf bank_mask:0xf bound_ctrl:1
	v_mov_b32_e32 v17, v28
	v_add_f32_dpp v18, v18, v18 row_ror:8 row_mask:0xf bank_mask:0xf bound_ctrl:1
	v_add_f32_dpp v16, v16, v16 row_ror:4 row_mask:0xf bank_mask:0xf bound_ctrl:1
	s_nop 0
	v_add_f32_dpp v18, v18, v18 row_ror:4 row_mask:0xf bank_mask:0xf bound_ctrl:1
	v_add_f32_dpp v16, v16, v16 row_ror:2 row_mask:0xf bank_mask:0xf bound_ctrl:1
	s_nop 0
	v_add_f32_dpp v18, v18, v18 row_ror:2 row_mask:0xf bank_mask:0xf bound_ctrl:1
	v_mov_b32_dpp v17, v16 row_ror:1 row_mask:0xf bank_mask:0xf
	s_nop 0
	v_mov_b32_dpp v19, v18 row_ror:1 row_mask:0xf bank_mask:0xf
	s_and_saveexec_b64 s[0:1], s[6:7]
	v_add_f32_e32 v16, v16, v17
	v_add_f32_e32 v17, v18, v19
	ds_write2_b32 v20, v16, v17 offset0:224 offset1:240
	s_or_b64 exec, exec, s[0:1]
	v_lshlrev_b64 v[16:17], 1, v[32:33]
	v_lshl_add_u64 v[18:19], s[40:41], 0, v[16:17]
	s_lshl_b32 s10, s58, 1
	v_lshl_add_u64 v[18:19], v[18:19], 0, s[10:11]
	v_lshlrev_b32_e32 v52, 1, v81
	v_mov_b32_e32 v53, v28
	v_lshl_add_u64 v[16:17], s[44:45], 0, v[16:17]
	v_sub_u32_e32 v95, 0x800, v85
	v_lshl_add_u64 v[54:55], v[18:19], 0, v[52:53]
	v_lshl_add_u64 v[56:57], v[36:37], 1, v[16:17]
	s_mov_b32 s21, 0
	s_mov_b32 s20, 0
	global_load_dword v253, v28, s[40:41]

.LBB0_1410:
	s_or_b64 exec, exec, s[0:1]
	v_add_u32_e32 v16, s20, v85
	s_bitcmp1_b32 s21, 0
	s_cselect_b32 s21, 0x5800, 0
	v_add_u32_e32 v250, s21, v31
	v_add_u32_e32 v172, s20, v30
	v_ashrrev_i32_e32 v173, 31, v172
	v_lshlrev_b64 v[172:173], 11, v[172:173]
	v_lshl_add_u64 v[172:173], v[54:55], 0, v[172:173]
	v_add_u32_e32 v17, 32, v16
	v_cmp_gt_i32_e32 vcc, s55, v17
	s_and_saveexec_b64 s[0:1], vcc
	s_cbranch_execz .LBB0_1416
	v_add3_u32 v16, v30, s20, 32
	v_mov_b64_e32 v[18:19], s[42:43]
	v_mad_i64_i32 v[22:23], s[20:21], v16, s3, v[18:19]
	v_lshl_add_u64 v[20:21], v[32:33], 1, v[22:23]
	v_lshl_add_u64 v[18:19], v[36:37], 1, v[20:21]
	v_add_co_u32_e32 v24, vcc, 0x1000, v18
	v_lshl_add_u64 v[22:23], v[40:41], 1, v[22:23]
	s_nop 0
	v_addc_co_u32_e32 v25, vcc, 0, v19, vcc
	global_load_dwordx2 v[42:43], v[18:19], off offset:3584
	global_load_dwordx2 v[38:39], v[24:25], off offset:128
	global_load_ushort v87, v[22:23], off
	v_mov_b32_e32 v29, v28
	v_cmp_lt_i32_e32 vcc, 0, v17
	s_waitcnt vmcnt(6)
	v_mov_b32_e32 v88, 0
	s_waitcnt vmcnt(5)
	v_mov_b64_e32 v[44:45], v[28:29]
	v_mov_b64_e32 v[46:47], v[28:29]
	s_and_saveexec_b64 s[20:21], vcc
	s_cbranch_execz .LBB0_1415
	v_add_co_u32_e32 v22, vcc, 0xfffff000, v18
	v_lshl_add_u64 v[20:21], v[20:21], 0, s[10:11]
	s_nop 0
	v_addc_co_u32_e32 v23, vcc, -1, v19, vcc
	v_mov_b32_e32 v53, v28
	v_lshl_add_u64 v[20:21], v[20:21], 0, v[52:53]
	global_load_dwordx2 v[46:47], v[22:23], off offset:-32
	global_load_ushort v88, v[20:21], off offset:-2976
	global_load_dwordx2 v[44:45], v[18:19], off offset:-3488

.LBB0_1416:
	s_or_b64 exec, exec, s[0:1]
	s_waitcnt lgkmcnt(0)
	s_barrier
	ds_read_b32 v250, v250 offset:21504
	v_lshl_add_u32 v17, v36, 2, s25
	v_add3_u32 v18, s25, v93, v94
	v_add_u32_e32 v25, 0x5000, v18
	v_bfe_u32 v19, v36, 2, 2
	ds_read2_b32 v[236:237], v25 offset0:0 offset1:16
	ds_read_b128 v[164:167], v17 offset:12288
	ds_read_b128 v[156:159], v17 offset:4096
	ds_read_b128 v[168:171], v17 offset:16384
	ds_read_b128 v[160:163], v17 offset:8192
	ds_read_b128 v[152:155], v17
	ds_read_b128 v[188:191], v17 offset:12544
	ds_read_b128 v[180:183], v17 offset:4352
	ds_read_b128 v[192:195], v17 offset:16640
	ds_read_b128 v[184:187], v17 offset:8448
	ds_read_b128 v[176:179], v17 offset:256
	s_waitcnt lgkmcnt(0)
	v_cvt_f16_f32_e32 v250, v250
	global_store_short v[172:173], v250, off offset:1024
	v_mul_f32_e32 v16, v164, v58
	v_fmac_f32_e32 v16, v165, v59
	v_fmac_f32_e32 v16, v166, v60
	v_fmac_f32_e32 v16, v167, v61
	v_mul_f32_e32 v20, v156, v236
	v_mul_f32_e32 v21, v157, v236
	v_add_f32_dpp v16, v16, v16 row_ror:8 row_mask:0xf bank_mask:0xf bound_ctrl:1
	v_mul_f32_e32 v22, v158, v236
	v_mul_f32_e32 v23, v159, v236
	v_add_f32_dpp v16, v16, v16 row_ror:4 row_mask:0xf bank_mask:0xf bound_ctrl:1
	ds_read2_b32 v[238:239], v25 offset0:32 offset1:48
	ds_read_b128 v[208:211], v17 offset:12800
	v_add_f32_dpp v16, v16, v16 row_ror:2 row_mask:0xf bank_mask:0xf bound_ctrl:1
	ds_read_b128 v[204:207], v17 offset:8704
	ds_read_b128 v[200:203], v17 offset:4608
	ds_read_b128 v[212:215], v17 offset:16896
	v_add_f32_dpp v16, v16, v16 row_ror:1 row_mask:0xf bank_mask:0xf bound_ctrl:1
	v_fma_f32 v20, -v168, v16, v20
	v_fma_f32 v21, -v169, v16, v21
	ds_read_b128 v[196:199], v17 offset:512
	v_fma_f32 v58, v160, v58, v20
	v_fma_f32 v22, -v170, v16, v22
	v_fma_f32 v59, v161, v59, v21
	v_fma_f32 v23, -v171, v16, v23
	v_fma_f32 v60, v162, v60, v22
	ds_read_b128 v[228:231], v17 offset:13056
	v_fma_f32 v61, v163, v61, v23
	v_mul_f32_e32 v16, v188, v58
	v_fmac_f32_e32 v16, v189, v59
	v_fmac_f32_e32 v16, v190, v60
	v_fmac_f32_e32 v16, v191, v61
	ds_read_b128 v[220:223], v17 offset:4864
	v_mul_f32_e32 v20, v180, v237
	v_mul_f32_e32 v21, v181, v237
	v_add_f32_dpp v16, v16, v16 row_ror:8 row_mask:0xf bank_mask:0xf bound_ctrl:1
	v_mul_f32_e32 v22, v182, v237
	v_mul_f32_e32 v23, v183, v237
	ds_read_b128 v[232:235], v17 offset:17152
	v_add_f32_dpp v16, v16, v16 row_ror:4 row_mask:0xf bank_mask:0xf bound_ctrl:1
	v_mul_f32_e32 v240, v152, v58
	v_fmac_f32_e32 v240, v153, v59
	v_add_f32_dpp v16, v16, v16 row_ror:2 row_mask:0xf bank_mask:0xf bound_ctrl:1
	v_fmac_f32_e32 v240, v154, v60
	ds_read_b128 v[224:227], v17 offset:8960
	v_fmac_f32_e32 v240, v155, v61
	v_add_f32_dpp v16, v16, v16 row_ror:1 row_mask:0xf bank_mask:0xf bound_ctrl:1
	v_fma_f32 v20, -v192, v16, v20
	v_fma_f32 v21, -v193, v16, v21
	v_fma_f32 v58, v184, v58, v20
	ds_read_b128 v[216:219], v17 offset:768
	v_fma_f32 v22, -v194, v16, v22
	v_fma_f32 v59, v185, v59, v21
	v_fma_f32 v23, -v195, v16, v23
	v_fma_f32 v60, v186, v60, v22
	v_fma_f32 v61, v187, v61, v23
	s_waitcnt lgkmcnt(0)
	v_mul_f32_e32 v16, v208, v58
	v_fmac_f32_e32 v16, v209, v59
	v_fmac_f32_e32 v16, v210, v60
	v_fmac_f32_e32 v16, v211, v61
	v_mul_f32_e32 v20, v200, v238
	v_mul_f32_e32 v21, v201, v238
	v_add_f32_dpp v16, v16, v16 row_ror:8 row_mask:0xf bank_mask:0xf bound_ctrl:1
	v_mul_f32_e32 v22, v202, v238
	v_mul_f32_e32 v23, v203, v238
	v_add_f32_dpp v16, v16, v16 row_ror:4 row_mask:0xf bank_mask:0xf bound_ctrl:1
	v_mul_f32_e32 v241, v176, v58
	v_fmac_f32_e32 v241, v177, v59
	v_add_f32_dpp v16, v16, v16 row_ror:2 row_mask:0xf bank_mask:0xf bound_ctrl:1
	ds_read2_b32 v[236:237], v25 offset0:64 offset1:80
	v_fmac_f32_e32 v241, v178, v60
	v_fmac_f32_e32 v241, v179, v61
	v_add_f32_dpp v16, v16, v16 row_ror:1 row_mask:0xf bank_mask:0xf bound_ctrl:1
	ds_read_b128 v[164:167], v17 offset:13312
	v_fma_f32 v20, -v212, v16, v20
	v_fma_f32 v21, -v213, v16, v21
	v_fma_f32 v58, v204, v58, v20
	ds_read_b128 v[156:159], v17 offset:5120
	v_fma_f32 v22, -v214, v16, v22
	v_fma_f32 v59, v205, v59, v21
	v_fma_f32 v23, -v215, v16, v23
	ds_read_b128 v[168:171], v17 offset:17408
	v_fma_f32 v60, v206, v60, v22
	v_fma_f32 v61, v207, v61, v23
	v_mul_f32_e32 v16, v228, v58
	v_fmac_f32_e32 v16, v229, v59
	ds_read_b128 v[160:163], v17 offset:9216
	v_fmac_f32_e32 v16, v230, v60
	v_fmac_f32_e32 v16, v231, v61
	v_mul_f32_e32 v20, v220, v239
	ds_read_b128 v[152:155], v17 offset:1024
	v_mul_f32_e32 v21, v221, v239
	v_add_f32_dpp v16, v16, v16 row_ror:8 row_mask:0xf bank_mask:0xf bound_ctrl:1
	v_mul_f32_e32 v22, v222, v239
	ds_read_b128 v[188:191], v17 offset:13568
	v_mul_f32_e32 v23, v223, v239
	v_add_f32_dpp v16, v16, v16 row_ror:4 row_mask:0xf bank_mask:0xf bound_ctrl:1
	v_mul_f32_e32 v242, v196, v58
	ds_read_b128 v[180:183], v17 offset:5376
	v_fmac_f32_e32 v242, v197, v59
	v_add_f32_dpp v16, v16, v16 row_ror:2 row_mask:0xf bank_mask:0xf bound_ctrl:1
	v_fmac_f32_e32 v242, v198, v60
	v_fmac_f32_e32 v242, v199, v61
	ds_read_b128 v[192:195], v17 offset:17664
	v_add_f32_dpp v16, v16, v16 row_ror:1 row_mask:0xf bank_mask:0xf bound_ctrl:1
	v_fma_f32 v20, -v232, v16, v20
	v_fma_f32 v21, -v233, v16, v21
	ds_read_b128 v[184:187], v17 offset:9472
	v_fma_f32 v58, v224, v58, v20
	v_fma_f32 v22, -v234, v16, v22
	v_fma_f32 v59, v225, v59, v21
	ds_read_b128 v[176:179], v17 offset:1280
	v_fma_f32 v23, -v235, v16, v23
	v_fma_f32 v60, v226, v60, v22
	v_fma_f32 v61, v227, v61, v23
	s_waitcnt lgkmcnt(0)
	v_mul_f32_e32 v16, v164, v58
	v_fmac_f32_e32 v16, v165, v59
	v_fmac_f32_e32 v16, v166, v60
	v_fmac_f32_e32 v16, v167, v61
	v_mul_f32_e32 v20, v156, v236
	v_mul_f32_e32 v21, v157, v236
	v_add_f32_dpp v16, v16, v16 row_ror:8 row_mask:0xf bank_mask:0xf bound_ctrl:1
	v_mul_f32_e32 v22, v158, v236
	v_mul_f32_e32 v23, v159, v236
	v_add_f32_dpp v16, v16, v16 row_ror:4 row_mask:0xf bank_mask:0xf bound_ctrl:1
	v_mul_f32_e32 v243, v216, v58
	v_fmac_f32_e32 v243, v217, v59
	v_add_f32_dpp v16, v16, v16 row_ror:2 row_mask:0xf bank_mask:0xf bound_ctrl:1
	ds_read2_b32 v[238:239], v25 offset0:96 offset1:112
	v_fmac_f32_e32 v243, v218, v60
	v_fmac_f32_e32 v243, v219, v61
	v_add_f32_dpp v16, v16, v16 row_ror:1 row_mask:0xf bank_mask:0xf bound_ctrl:1
	ds_read_b128 v[208:211], v17 offset:13824
	v_fma_f32 v20, -v168, v16, v20
	v_fma_f32 v21, -v169, v16, v21
	v_fma_f32 v58, v160, v58, v20
	ds_read_b128 v[200:203], v17 offset:5632
	v_fma_f32 v22, -v170, v16, v22
	v_fma_f32 v59, v161, v59, v21
	v_fma_f32 v23, -v171, v16, v23
	ds_read_b128 v[212:215], v17 offset:17920
	v_fma_f32 v60, v162, v60, v22
	v_fma_f32 v61, v163, v61, v23
	v_mul_f32_e32 v16, v188, v58
	v_fmac_f32_e32 v16, v189, v59
	ds_read_b128 v[204:207], v17 offset:9728
	v_fmac_f32_e32 v16, v190, v60
	v_fmac_f32_e32 v16, v191, v61
	v_mul_f32_e32 v20, v180, v237
	ds_read_b128 v[196:199], v17 offset:1536
	v_mul_f32_e32 v21, v181, v237
	v_add_f32_dpp v16, v16, v16 row_ror:8 row_mask:0xf bank_mask:0xf bound_ctrl:1
	v_mul_f32_e32 v22, v182, v237
	ds_read_b128 v[228:231], v17 offset:14080
	v_mul_f32_e32 v23, v183, v237
	v_add_f32_dpp v16, v16, v16 row_ror:4 row_mask:0xf bank_mask:0xf bound_ctrl:1
	v_mul_f32_e32 v244, v152, v58
	ds_read_b128 v[220:223], v17 offset:5888
	v_fmac_f32_e32 v244, v153, v59
	v_add_f32_dpp v16, v16, v16 row_ror:2 row_mask:0xf bank_mask:0xf bound_ctrl:1
	v_fmac_f32_e32 v244, v154, v60
	v_fmac_f32_e32 v244, v155, v61
	ds_read_b128 v[232:235], v17 offset:18176
	v_add_f32_dpp v16, v16, v16 row_ror:1 row_mask:0xf bank_mask:0xf bound_ctrl:1
	v_fma_f32 v20, -v192, v16, v20
	v_fma_f32 v21, -v193, v16, v21
	ds_read_b128 v[224:227], v17 offset:9984
	v_fma_f32 v58, v184, v58, v20
	v_fma_f32 v22, -v194, v16, v22
	v_fma_f32 v59, v185, v59, v21
	ds_read_b128 v[216:219], v17 offset:1792
	v_fma_f32 v23, -v195, v16, v23
	v_fma_f32 v60, v186, v60, v22
	v_fma_f32 v61, v187, v61, v23
	s_waitcnt lgkmcnt(0)
	v_mul_f32_e32 v16, v208, v58
	v_fmac_f32_e32 v16, v209, v59
	v_fmac_f32_e32 v16, v210, v60
	v_fmac_f32_e32 v16, v211, v61
	v_mul_f32_e32 v20, v200, v238
	v_mul_f32_e32 v21, v201, v238
	v_add_f32_dpp v16, v16, v16 row_ror:8 row_mask:0xf bank_mask:0xf bound_ctrl:1
	v_mul_f32_e32 v22, v202, v238
	v_mul_f32_e32 v23, v203, v238
	v_add_f32_dpp v16, v16, v16 row_ror:4 row_mask:0xf bank_mask:0xf bound_ctrl:1
	v_mul_f32_e32 v245, v176, v58
	v_fmac_f32_e32 v245, v177, v59
	v_add_f32_dpp v16, v16, v16 row_ror:2 row_mask:0xf bank_mask:0xf bound_ctrl:1
	ds_read2_b32 v[236:237], v25 offset0:128 offset1:144
	v_fmac_f32_e32 v245, v178, v60
	v_fmac_f32_e32 v245, v179, v61
	v_add_f32_dpp v16, v16, v16 row_ror:1 row_mask:0xf bank_mask:0xf bound_ctrl:1
	ds_read_b128 v[164:167], v17 offset:14336
	v_fma_f32 v20, -v212, v16, v20
	v_fma_f32 v21, -v213, v16, v21
	v_fma_f32 v58, v204, v58, v20
	ds_read_b128 v[156:159], v17 offset:6144
	v_fma_f32 v22, -v214, v16, v22
	v_fma_f32 v59, v205, v59, v21
	v_fma_f32 v23, -v215, v16, v23
	ds_read_b128 v[168:171], v17 offset:18432
	v_fma_f32 v60, v206, v60, v22
	v_fma_f32 v61, v207, v61, v23
	v_mul_f32_e32 v16, v228, v58
	v_fmac_f32_e32 v16, v229, v59
	ds_read_b128 v[160:163], v17 offset:10240
	v_fmac_f32_e32 v16, v230, v60
	v_fmac_f32_e32 v16, v231, v61
	v_mul_f32_e32 v20, v220, v239
	ds_read_b128 v[152:155], v17 offset:2048
	v_mul_f32_e32 v21, v221, v239
	v_add_f32_dpp v16, v16, v16 row_ror:8 row_mask:0xf bank_mask:0xf bound_ctrl:1
	v_mul_f32_e32 v22, v222, v239
	ds_read_b128 v[188:191], v17 offset:14592
	v_mul_f32_e32 v23, v223, v239
	v_add_f32_dpp v16, v16, v16 row_ror:4 row_mask:0xf bank_mask:0xf bound_ctrl:1
	v_mul_f32_e32 v246, v196, v58
	ds_read_b128 v[180:183], v17 offset:6400
	v_fmac_f32_e32 v246, v197, v59
	v_add_f32_dpp v16, v16, v16 row_ror:2 row_mask:0xf bank_mask:0xf bound_ctrl:1
	v_fmac_f32_e32 v246, v198, v60
	v_fmac_f32_e32 v246, v199, v61
	ds_read_b128 v[192:195], v17 offset:18688
	v_add_f32_dpp v16, v16, v16 row_ror:1 row_mask:0xf bank_mask:0xf bound_ctrl:1
	v_fma_f32 v20, -v232, v16, v20
	v_fma_f32 v21, -v233, v16, v21
	ds_read_b128 v[184:187], v17 offset:10496
	v_fma_f32 v58, v224, v58, v20
	v_fma_f32 v22, -v234, v16, v22
	v_fma_f32 v59, v225, v59, v21
	ds_read_b128 v[176:179], v17 offset:2304
	v_fma_f32 v23, -v235, v16, v23
	v_fma_f32 v60, v226, v60, v22
	v_fma_f32 v61, v227, v61, v23
	s_waitcnt lgkmcnt(0)
	v_mul_f32_e32 v16, v164, v58
	v_fmac_f32_e32 v16, v165, v59
	v_fmac_f32_e32 v16, v166, v60
	v_fmac_f32_e32 v16, v167, v61
	v_mul_f32_e32 v20, v156, v236
	v_mul_f32_e32 v21, v157, v236
	v_add_f32_dpp v16, v16, v16 row_ror:8 row_mask:0xf bank_mask:0xf bound_ctrl:1
	v_mul_f32_e32 v22, v158, v236
	v_mul_f32_e32 v23, v159, v236
	v_add_f32_dpp v16, v16, v16 row_ror:4 row_mask:0xf bank_mask:0xf bound_ctrl:1
	v_mul_f32_e32 v247, v216, v58
	v_fmac_f32_e32 v247, v217, v59
	v_add_f32_dpp v16, v16, v16 row_ror:2 row_mask:0xf bank_mask:0xf bound_ctrl:1
	ds_read2_b32 v[238:239], v25 offset0:160 offset1:176
	v_fmac_f32_e32 v247, v218, v60
	v_fmac_f32_e32 v247, v219, v61
	v_add_f32_dpp v16, v16, v16 row_ror:1 row_mask:0xf bank_mask:0xf bound_ctrl:1
	ds_read_b128 v[208:211], v17 offset:14848
	v_fma_f32 v20, -v168, v16, v20
	v_fma_f32 v21, -v169, v16, v21
	v_fma_f32 v58, v160, v58, v20
	ds_read_b128 v[200:203], v17 offset:6656
	v_fma_f32 v22, -v170, v16, v22
	v_fma_f32 v59, v161, v59, v21
	v_fma_f32 v23, -v171, v16, v23
	ds_read_b128 v[212:215], v17 offset:18944
	v_fma_f32 v60, v162, v60, v22
	v_fma_f32 v61, v163, v61, v23
	v_mul_f32_e32 v16, v188, v58
	v_fmac_f32_e32 v16, v189, v59
	ds_read_b128 v[204:207], v17 offset:10752
	v_fmac_f32_e32 v16, v190, v60
	v_fmac_f32_e32 v16, v191, v61
	v_mul_f32_e32 v20, v180, v237
	ds_read_b128 v[196:199], v17 offset:2560
	v_mul_f32_e32 v21, v181, v237
	v_add_f32_dpp v16, v16, v16 row_ror:8 row_mask:0xf bank_mask:0xf bound_ctrl:1
	v_mul_f32_e32 v22, v182, v237
	ds_read_b128 v[228:231], v17 offset:15104
	v_mul_f32_e32 v23, v183, v237
	v_add_f32_dpp v16, v16, v16 row_ror:4 row_mask:0xf bank_mask:0xf bound_ctrl:1
	v_mul_f32_e32 v248, v152, v58
	ds_read_b128 v[220:223], v17 offset:6912
	v_fmac_f32_e32 v248, v153, v59
	v_add_f32_dpp v16, v16, v16 row_ror:2 row_mask:0xf bank_mask:0xf bound_ctrl:1
	v_fmac_f32_e32 v248, v154, v60
	v_fmac_f32_e32 v248, v155, v61
	ds_read_b128 v[232:235], v17 offset:19200
	v_add_f32_dpp v16, v16, v16 row_ror:1 row_mask:0xf bank_mask:0xf bound_ctrl:1
	v_fma_f32 v20, -v192, v16, v20
	v_fma_f32 v21, -v193, v16, v21
	ds_read_b128 v[224:227], v17 offset:11008
	v_fma_f32 v58, v184, v58, v20
	v_fma_f32 v22, -v194, v16, v22
	v_fma_f32 v59, v185, v59, v21
	ds_read_b128 v[216:219], v17 offset:2816
	v_fma_f32 v23, -v195, v16, v23
	v_fma_f32 v60, v186, v60, v22
	v_fma_f32 v61, v187, v61, v23
	s_waitcnt lgkmcnt(0)
	v_mul_f32_e32 v16, v208, v58
	v_fmac_f32_e32 v16, v209, v59
	v_fmac_f32_e32 v16, v210, v60
	v_fmac_f32_e32 v16, v211, v61
	v_mul_f32_e32 v20, v200, v238
	v_mul_f32_e32 v21, v201, v238
	v_add_f32_dpp v16, v16, v16 row_ror:8 row_mask:0xf bank_mask:0xf bound_ctrl:1
	v_mul_f32_e32 v22, v202, v238
	v_mul_f32_e32 v23, v203, v238
	v_add_f32_dpp v16, v16, v16 row_ror:4 row_mask:0xf bank_mask:0xf bound_ctrl:1
	v_mul_f32_e32 v249, v176, v58
	v_fmac_f32_e32 v249, v177, v59
	v_add_f32_dpp v16, v16, v16 row_ror:2 row_mask:0xf bank_mask:0xf bound_ctrl:1
	ds_read2_b32 v[236:237], v25 offset0:192 offset1:208
	v_fmac_f32_e32 v249, v178, v60
	v_fmac_f32_e32 v249, v179, v61
	v_add_f32_dpp v16, v16, v16 row_ror:1 row_mask:0xf bank_mask:0xf bound_ctrl:1
	ds_read_b128 v[164:167], v17 offset:15360
	v_fma_f32 v20, -v212, v16, v20
	v_fma_f32 v21, -v213, v16, v21
	v_fma_f32 v58, v204, v58, v20
	ds_read_b128 v[156:159], v17 offset:7168
	v_fma_f32 v22, -v214, v16, v22
	v_fma_f32 v59, v205, v59, v21
	v_fma_f32 v23, -v215, v16, v23
	ds_read_b128 v[168:171], v17 offset:19456
	v_fma_f32 v60, v206, v60, v22
	v_fma_f32 v61, v207, v61, v23
	v_mul_f32_e32 v16, v228, v58
	v_fmac_f32_e32 v16, v229, v59
	ds_read_b128 v[160:163], v17 offset:11264
	v_fmac_f32_e32 v16, v230, v60
	v_fmac_f32_e32 v16, v231, v61
	v_mul_f32_e32 v20, v220, v239
	ds_read_b128 v[152:155], v17 offset:3072
	v_mul_f32_e32 v21, v221, v239
	v_add_f32_dpp v16, v16, v16 row_ror:8 row_mask:0xf bank_mask:0xf bound_ctrl:1
	v_mul_f32_e32 v22, v222, v239
	ds_read_b128 v[188:191], v17 offset:15616
	v_mul_f32_e32 v23, v223, v239
	v_add_f32_dpp v16, v16, v16 row_ror:4 row_mask:0xf bank_mask:0xf bound_ctrl:1
	v_mul_f32_e32 v150, v196, v58
	ds_read_b128 v[180:183], v17 offset:7424
	v_fmac_f32_e32 v150, v197, v59
	v_add_f32_dpp v16, v16, v16 row_ror:2 row_mask:0xf bank_mask:0xf bound_ctrl:1
	v_fmac_f32_e32 v150, v198, v60
	v_fmac_f32_e32 v150, v199, v61
	ds_read_b128 v[192:195], v17 offset:19712
	v_add_f32_dpp v16, v16, v16 row_ror:1 row_mask:0xf bank_mask:0xf bound_ctrl:1
	v_fma_f32 v20, -v232, v16, v20
	v_fma_f32 v21, -v233, v16, v21
	ds_read_b128 v[184:187], v17 offset:11520
	v_fma_f32 v58, v224, v58, v20
	v_fma_f32 v22, -v234, v16, v22
	v_fma_f32 v59, v225, v59, v21
	ds_read_b128 v[176:179], v17 offset:3328
	v_fma_f32 v23, -v235, v16, v23
	v_fma_f32 v60, v226, v60, v22
	v_fma_f32 v61, v227, v61, v23
	s_waitcnt lgkmcnt(0)
	v_mul_f32_e32 v16, v164, v58
	v_fmac_f32_e32 v16, v165, v59
	v_fmac_f32_e32 v16, v166, v60
	v_fmac_f32_e32 v16, v167, v61
	v_mul_f32_e32 v20, v156, v236
	v_mul_f32_e32 v21, v157, v236
	v_add_f32_dpp v16, v16, v16 row_ror:8 row_mask:0xf bank_mask:0xf bound_ctrl:1
	v_mul_f32_e32 v22, v158, v236
	v_mul_f32_e32 v23, v159, v236
	v_add_f32_dpp v16, v16, v16 row_ror:4 row_mask:0xf bank_mask:0xf bound_ctrl:1
	v_mul_f32_e32 v151, v216, v58
	v_fmac_f32_e32 v151, v217, v59
	v_add_f32_dpp v16, v16, v16 row_ror:2 row_mask:0xf bank_mask:0xf bound_ctrl:1
	ds_read2_b32 v[238:239], v25 offset0:224 offset1:240
	v_fmac_f32_e32 v151, v218, v60
	v_fmac_f32_e32 v151, v219, v61
	v_add_f32_dpp v16, v16, v16 row_ror:1 row_mask:0xf bank_mask:0xf bound_ctrl:1
	ds_read_b128 v[208:211], v17 offset:15872
	v_fma_f32 v20, -v168, v16, v20
	v_fma_f32 v21, -v169, v16, v21
	v_fma_f32 v58, v160, v58, v20
	ds_read_b128 v[200:203], v17 offset:7680
	v_fma_f32 v22, -v170, v16, v22
	v_fma_f32 v59, v161, v59, v21
	v_fma_f32 v23, -v171, v16, v23
	ds_read_b128 v[212:215], v17 offset:19968
	v_fma_f32 v60, v162, v60, v22
	v_fma_f32 v61, v163, v61, v23
	v_mul_f32_e32 v16, v188, v58
	v_fmac_f32_e32 v16, v189, v59
	ds_read_b128 v[204:207], v17 offset:11776
	v_fmac_f32_e32 v16, v190, v60
	v_fmac_f32_e32 v16, v191, v61
	v_mul_f32_e32 v20, v180, v237
	ds_read_b128 v[196:199], v17 offset:3584
	v_mul_f32_e32 v21, v181, v237
	v_add_f32_dpp v16, v16, v16 row_ror:8 row_mask:0xf bank_mask:0xf bound_ctrl:1
	v_mul_f32_e32 v22, v182, v237
	ds_read_b128 v[228:231], v17 offset:16128
	v_mul_f32_e32 v23, v183, v237
	v_add_f32_dpp v16, v16, v16 row_ror:4 row_mask:0xf bank_mask:0xf bound_ctrl:1
	v_mul_f32_e32 v26, v152, v58
	ds_read_b128 v[220:223], v17 offset:7936
	v_fmac_f32_e32 v26, v153, v59
	v_add_f32_dpp v16, v16, v16 row_ror:2 row_mask:0xf bank_mask:0xf bound_ctrl:1
	v_fmac_f32_e32 v26, v154, v60
	v_fmac_f32_e32 v26, v155, v61
	ds_read_b128 v[232:235], v17 offset:20224
	v_add_f32_dpp v16, v16, v16 row_ror:1 row_mask:0xf bank_mask:0xf bound_ctrl:1
	v_fma_f32 v20, -v192, v16, v20
	v_fma_f32 v21, -v193, v16, v21
	ds_read_b128 v[224:227], v17 offset:12032
	v_fma_f32 v58, v184, v58, v20
	v_fma_f32 v22, -v194, v16, v22
	v_fma_f32 v59, v185, v59, v21
	ds_read_b128 v[216:219], v17 offset:3840
	v_fma_f32 v23, -v195, v16, v23
	v_fma_f32 v60, v186, v60, v22
	v_fma_f32 v61, v187, v61, v23
	s_waitcnt lgkmcnt(0)
	v_mul_f32_e32 v16, v208, v58
	v_fmac_f32_e32 v16, v209, v59
	v_fmac_f32_e32 v16, v210, v60
	v_fmac_f32_e32 v16, v211, v61
	v_mul_f32_e32 v20, v200, v238
	v_mul_f32_e32 v21, v201, v238
	v_add_f32_dpp v16, v16, v16 row_ror:8 row_mask:0xf bank_mask:0xf bound_ctrl:1
	v_mul_f32_e32 v22, v202, v238
	v_mul_f32_e32 v23, v203, v238
	v_add_f32_dpp v16, v16, v16 row_ror:4 row_mask:0xf bank_mask:0xf bound_ctrl:1
	v_mul_f32_e32 v27, v176, v58
	v_fmac_f32_e32 v27, v177, v59
	v_add_f32_dpp v16, v16, v16 row_ror:2 row_mask:0xf bank_mask:0xf bound_ctrl:1
	v_fmac_f32_e32 v27, v178, v60
	v_fmac_f32_e32 v27, v179, v61
	v_add_f32_dpp v16, v16, v16 row_ror:1 row_mask:0xf bank_mask:0xf bound_ctrl:1
	v_fma_f32 v20, -v212, v16, v20
	v_fma_f32 v21, -v213, v16, v21
	v_fma_f32 v58, v204, v58, v20
	v_fma_f32 v22, -v214, v16, v22
	v_fma_f32 v59, v205, v59, v21
	v_fma_f32 v23, -v215, v16, v23
	v_fma_f32 v60, v206, v60, v22
	v_fma_f32 v61, v207, v61, v23
	v_mul_f32_e32 v16, v228, v58
	v_fmac_f32_e32 v16, v229, v59
	v_fmac_f32_e32 v16, v230, v60
	v_fmac_f32_e32 v16, v231, v61
	v_mul_f32_e32 v20, v220, v239
	v_mul_f32_e32 v21, v221, v239
	v_add_f32_dpp v16, v16, v16 row_ror:8 row_mask:0xf bank_mask:0xf bound_ctrl:1
	v_mul_f32_e32 v22, v222, v239
	v_mul_f32_e32 v23, v223, v239
	v_add_f32_dpp v16, v16, v16 row_ror:4 row_mask:0xf bank_mask:0xf bound_ctrl:1
	v_mul_f32_e32 v62, v196, v58
	v_fmac_f32_e32 v62, v197, v59
	v_add_f32_dpp v16, v16, v16 row_ror:2 row_mask:0xf bank_mask:0xf bound_ctrl:1
	v_fmac_f32_e32 v62, v198, v60
	v_fmac_f32_e32 v62, v199, v61
	v_add_f32_dpp v16, v16, v16 row_ror:1 row_mask:0xf bank_mask:0xf bound_ctrl:1
	v_fma_f32 v20, -v232, v16, v20
	v_fma_f32 v21, -v233, v16, v21
	v_fma_f32 v58, v224, v58, v20
	v_fma_f32 v22, -v234, v16, v22
	v_fma_f32 v59, v225, v59, v21
	v_fma_f32 v23, -v235, v16, v23
	v_fma_f32 v60, v226, v60, v22
	v_fma_f32 v61, v227, v61, v23
	v_mul_f32_e32 v63, v216, v58
	v_fmac_f32_e32 v63, v217, v59
	v_fmac_f32_e32 v63, v218, v60
	v_fmac_f32_e32 v63, v219, v61
	v_add_f32_dpp v240, v240, v240 row_ror:8 row_mask:0xf bank_mask:0x3
	v_add_f32_dpp v241, v241, v241 row_ror:8 row_mask:0xf bank_mask:0x3
	v_add_f32_dpp v242, v242, v242 row_ror:8 row_mask:0xf bank_mask:0x3
	v_add_f32_dpp v243, v243, v243 row_ror:8 row_mask:0xf bank_mask:0x3
	v_add_f32_dpp v244, v244, v244 row_ror:8 row_mask:0xf bank_mask:0x3
	v_add_f32_dpp v245, v245, v245 row_ror:8 row_mask:0xf bank_mask:0x3
	v_add_f32_dpp v246, v246, v246 row_ror:8 row_mask:0xf bank_mask:0x3
	v_add_f32_dpp v247, v247, v247 row_ror:8 row_mask:0xf bank_mask:0x3
	v_add_f32_dpp v240, v248, v248 row_ror:8 row_mask:0xf bank_mask:0xc
	v_add_f32_dpp v241, v249, v249 row_ror:8 row_mask:0xf bank_mask:0xc
	v_add_f32_dpp v242, v150, v150 row_ror:8 row_mask:0xf bank_mask:0xc
	v_add_f32_dpp v243, v151, v151 row_ror:8 row_mask:0xf bank_mask:0xc
	v_add_f32_dpp v244, v26, v26 row_ror:8 row_mask:0xf bank_mask:0xc
	v_add_f32_dpp v245, v27, v27 row_ror:8 row_mask:0xf bank_mask:0xc
	v_add_f32_dpp v246, v62, v62 row_ror:8 row_mask:0xf bank_mask:0xc
	v_add_f32_dpp v247, v63, v63 row_ror:8 row_mask:0xf bank_mask:0xc
	v_add_f32_dpp v240, v240, v240 row_ror:12 row_mask:0xf bank_mask:0x5
	v_add_f32_dpp v241, v241, v241 row_ror:12 row_mask:0xf bank_mask:0x5
	v_add_f32_dpp v242, v242, v242 row_ror:12 row_mask:0xf bank_mask:0x5
	v_add_f32_dpp v243, v243, v243 row_ror:12 row_mask:0xf bank_mask:0x5
	v_add_f32_dpp v240, v244, v244 row_ror:4 row_mask:0xf bank_mask:0xa
	v_add_f32_dpp v241, v245, v245 row_ror:4 row_mask:0xf bank_mask:0xa
	v_add_f32_dpp v242, v246, v246 row_ror:4 row_mask:0xf bank_mask:0xa
	v_add_f32_dpp v243, v247, v247 row_ror:4 row_mask:0xf bank_mask:0xa
	v_lshl_add_u32 v25, v36, 4, v18
	v_add_f32_dpp v240, v240, v240 quad_perm:[1,0,3,2] row_mask:0xf bank_mask:0xf
	v_add_f32_dpp v241, v241, v241 quad_perm:[1,0,3,2] row_mask:0xf bank_mask:0xf
	v_add_f32_dpp v242, v242, v242 quad_perm:[1,0,3,2] row_mask:0xf bank_mask:0xf
	v_add_f32_dpp v243, v243, v243 quad_perm:[1,0,3,2] row_mask:0xf bank_mask:0xf
	v_add_f32_dpp v240, v240, v240 quad_perm:[2,3,0,1] row_mask:0xf bank_mask:0xf
	v_add_f32_dpp v241, v241, v241 quad_perm:[2,3,0,1] row_mask:0xf bank_mask:0xf
	v_add_f32_dpp v242, v242, v242 quad_perm:[2,3,0,1] row_mask:0xf bank_mask:0xf
	v_add_f32_dpp v243, v243, v243 quad_perm:[2,3,0,1] row_mask:0xf bank_mask:0xf
	v_cmp_eq_u32_e32 vcc, 1, v19
	s_nop 1
	v_cndmask_b32_e32 v24, v240, v241, vcc
	v_cmp_eq_u32_e32 vcc, 2, v19
	s_nop 1
	v_cndmask_b32_e32 v24, v24, v242, vcc
	v_cmp_eq_u32_e32 vcc, 3, v19
	s_nop 1
	v_cndmask_b32_e32 v24, v24, v243, vcc
	ds_write_b32 v25, v24 offset:21504
	s_cmpk_eq_i32 s9, 0x7e0
	s_cbranch_scc1 .LBB0_1434
	s_mov_b32 s21, s24
	s_mov_b32 s20, s9
	s_branch .LBB0_1406
